# K-loop LDS-DMA rebalanced to 4 loads per load segment (A half-0 stages moved one phase later, counted waits 8/6/8/6), SGPR-base addressing
# speedup vs baseline: 1.0107x; 1.0086x over previous
; #define PG8_STAGE(bufoff, gbase, voff) do { _Pragma("unroll") for (int _i = 0; _i < 2; ++_i) \
;         __builtin_amdgcn_global_load_lds((const unsigned*)((const char*)(gbase) + (voff)[_i]), (LAS unsigned*)(lds + (bufoff) + ldsw + _i * 8192), 16, 0, 0); } while (0)
; #define PG8_LDA(dst, b, h) do { _Pragma("unroll") for (int m = 0; m < 4; ++m) _Pragma("unroll") for (int k = 0; k < 2; ++k) dst[m][k] = *(const LAS bf16x8*)(lds + PG8_SA(b, h) + aoff + m * 2048 + k * 1024); } while (0)
; #define PG8_LDB(dst, b, h) do { _Pragma("unroll") for (int n = 0; n < 2; ++n) _Pragma("unroll") for (int k = 0; k < 2; ++k) dst[n][k] = *(const LAS bf16x8*)(lds + PG8_SB(b, h) + boff + n * 2048 + k * 1024); } while (0)
; #define PG8_MMA(ai, bj, At, Bt) do { __builtin_amdgcn_s_setprio(1); _Pragma("unroll") for (int m = 0; m < 4; ++m) _Pragma("unroll") for (int n = 0; n < 2; ++n) _Pragma("unroll") for (int k = 0; k < 2; ++k) \
;         acc[ai][bj][m][n] = __builtin_amdgcn_mfma_f32_16x16x32_bf16(Bt[n][k], At[m][k], acc[ai][bj][m][n], 0, 0, 0); __builtin_amdgcn_s_setprio(0); } while (0)
; #define PG8_WAIT_V(n) asm volatile("s_waitcnt vmcnt(" #n ")" ::: "memory")
; #define PG8_WAIT_L(n) asm volatile("s_waitcnt lgkmcnt(" #n ")" ::: "memory")
; #define PG8_BAR __builtin_amdgcn_s_barrier()
; #define PG8_SCHED __builtin_amdgcn_sched_barrier(0)
; template <class Epi, class Sched, bool ALIGN_EPI = false, bool SP2 = false>
; __device__ __forceinline__ void gemm_phase(LAS unsigned char* lds, const Gemm g, const Sched& S, const Epi& E) {
;     ...
;             PG8_LDB(B0, 0, 0); PG8_LDB(B1, 0, 1); PG8_SCHED; PG8_LDA(At, 0, 0); PG8_STAGE(PG8_SA(1, 1), a1 + hstep, voffA);
;             PG8_WAIT_V(8); PG8_WAIT_L(0); PG8_BAR; PG8_MMA(0, 0, At, B0); PG8_MMA(0, 1, At, B1); PG8_BAR; PG8_SCHED;
;             PG8_LDA(At, 0, 1); PG8_STAGE(PG8_SB(0, 0), b2, voffB); PG8_STAGE(PG8_SB(0, 1), b2 + hstep, voffB); PG8_STAGE(PG8_SA(0, 0), a2, voffA);
.LBB0_260:
	s_add_u32 s100, s10, 0xfff00000
	s_addc_u32 s101, s11, -1
	s_add_u32 s12, s10, 0xfff00080
	s_addc_u32 s13, s11, -1
	s_add_i32 s44, 0, 0x10000
	s_cmp_eq_u32 s42, 60
	s_cselect_b32 s15, s2, s13
	s_cselect_b32 s14, s3, s12
	v_add_u32_e32 v146, s44, v149
	s_cselect_b32 s13, s17, s41
	s_cselect_b32 s12, s23, s25
	s_add_i32 s48, 0, 0x14000
	ds_read_b128 v[142:145], v146
	ds_read_b128 v[156:159], v146 offset:1024
	ds_read_b128 v[160:163], v146 offset:2048
	ds_read_b128 v[164:167], v146 offset:3072
	v_add_u32_e32 v146, s48, v149
	ds_read_b128 v[168:171], v146
	ds_read_b128 v[172:175], v146 offset:1024
	ds_read_b128 v[176:179], v146 offset:2048
	ds_read_b128 v[180:183], v146 offset:3072
	s_add_i32 m0, s34, 0xc000
	ds_read_b128 v[184:187], v155
	ds_read_b128 v[188:191], v155 offset:1024
	ds_read_b128 v[198:201], v155 offset:2048
	ds_read_b128 v[202:205], v155 offset:3072
	ds_read_b128 v[206:209], v155 offset:4096
	ds_read_b128 v[210:213], v155 offset:5120
	ds_read_b128 v[214:217], v155 offset:6144
	ds_read_b128 v[228:231], v155 offset:7168
	s_mov_b32 m0, s38
	s_nop 0
	global_load_lds_dwordx4 v132, s[100:101]
	s_mov_b32 m0, s39
	s_nop 0
	global_load_lds_dwordx4 v130, s[100:101]
	s_add_i32 m0, s34, 0xc000
	s_nop 0
	global_load_lds_dwordx4 v138, s[10:11]
	s_add_i32 m0, s34, 0xe000
	s_nop 0
	global_load_lds_dwordx4 v140, s[10:11]
	s_waitcnt vmcnt(8)
	s_waitcnt lgkmcnt(0)
	s_barrier
	s_setprio 1
	s_waitcnt lgkmcnt(0)
	v_mfma_f32_16x16x32_bf16 v[124:127], v[142:145], v[184:187], v[124:127]
	v_mfma_f32_16x16x32_bf16 v[120:123], v[160:163], v[184:187], v[120:123]
	v_mfma_f32_16x16x32_bf16 v[108:111], v[142:145], v[198:201], v[108:111]
	v_mfma_f32_16x16x32_bf16 v[104:107], v[160:163], v[198:201], v[104:107]
	v_mfma_f32_16x16x32_bf16 v[92:95], v[142:145], v[206:209], v[92:95]
	v_mfma_f32_16x16x32_bf16 v[88:91], v[160:163], v[206:209], v[88:91]
	v_mfma_f32_16x16x32_bf16 v[76:79], v[142:145], v[214:217], v[76:79]
	v_mfma_f32_16x16x32_bf16 v[72:75], v[160:163], v[214:217], v[72:75]
	v_mfma_f32_16x16x32_bf16 v[124:127], v[156:159], v[188:191], v[124:127]
	v_mfma_f32_16x16x32_bf16 v[120:123], v[164:167], v[188:191], v[120:123]
	v_mfma_f32_16x16x32_bf16 v[108:111], v[156:159], v[202:205], v[108:111]
	v_mfma_f32_16x16x32_bf16 v[104:107], v[164:167], v[202:205], v[104:107]
	v_mfma_f32_16x16x32_bf16 v[92:95], v[156:159], v[210:213], v[92:95]
	v_mfma_f32_16x16x32_bf16 v[88:91], v[164:167], v[210:213], v[88:91]
	v_mfma_f32_16x16x32_bf16 v[76:79], v[156:159], v[228:231], v[76:79]
	v_mfma_f32_16x16x32_bf16 v[72:75], v[164:167], v[228:231], v[72:75]
	s_setprio 0
	s_setprio 1
	v_mfma_f32_16x16x32_bf16 v[116:119], v[168:171], v[184:187], v[116:119]
	v_mfma_f32_16x16x32_bf16 v[112:115], v[176:179], v[184:187], v[112:115]
	v_mfma_f32_16x16x32_bf16 v[100:103], v[168:171], v[198:201], v[100:103]
	v_mfma_f32_16x16x32_bf16 v[96:99], v[176:179], v[198:201], v[96:99]
	v_mfma_f32_16x16x32_bf16 v[84:87], v[168:171], v[206:209], v[84:87]
	v_mfma_f32_16x16x32_bf16 v[80:83], v[176:179], v[206:209], v[80:83]
	v_mfma_f32_16x16x32_bf16 v[68:71], v[168:171], v[214:217], v[68:71]
	v_mfma_f32_16x16x32_bf16 v[64:67], v[176:179], v[214:217], v[64:67]
	v_mfma_f32_16x16x32_bf16 v[116:119], v[172:175], v[188:191], v[116:119]
	v_mfma_f32_16x16x32_bf16 v[112:115], v[180:183], v[188:191], v[112:115]
	v_mfma_f32_16x16x32_bf16 v[100:103], v[172:175], v[202:205], v[100:103]
	v_mfma_f32_16x16x32_bf16 v[96:99], v[180:183], v[202:205], v[96:99]
	v_mfma_f32_16x16x32_bf16 v[84:87], v[172:175], v[210:213], v[84:87]
	v_mfma_f32_16x16x32_bf16 v[80:83], v[180:183], v[210:213], v[80:83]
	v_mfma_f32_16x16x32_bf16 v[68:71], v[172:175], v[228:231], v[68:71]
	v_mfma_f32_16x16x32_bf16 v[64:67], v[180:183], v[228:231], v[64:67]
	s_setprio 0
	s_barrier
	s_add_u32 s98, s12, 0x80
	s_addc_u32 s99, s13, 0
	s_add_i32 s44, s44, s7
	s_mov_b32 m0, s44
	ds_read_b128 v[184:187], v155 offset:16384
	ds_read_b128 v[188:191], v155 offset:17408
	ds_read_b128 v[198:201], v155 offset:18432
	ds_read_b128 v[202:205], v155 offset:19456
	ds_read_b128 v[206:209], v155 offset:20480
	ds_read_b128 v[210:213], v155 offset:21504
	ds_read_b128 v[214:217], v155 offset:22528
	ds_read_b128 v[228:231], v155 offset:23552
	global_load_lds_dwordx4 v196, s[12:13]
	s_add_i32 m0, s44, 0x2000
	s_add_u32 s46, s12, 0x100000
	s_addc_u32 s47, s13, 0
	s_add_i32 s44, s48, s7
	global_load_lds_dwordx4 v128, s[12:13]
	s_mov_b32 m0, s44
	s_nop 0
	global_load_lds_dwordx4 v196, s[46:47]
	s_add_i32 m0, s44, 0x2000
	s_nop 0
	global_load_lds_dwordx4 v128, s[46:47]
	s_waitcnt vmcnt(6)
	s_waitcnt lgkmcnt(0)
	s_barrier
; #define PG8_STAGE(bufoff, gbase, voff) do { _Pragma("unroll") for (int _i = 0; _i < 2; ++_i) \
;         __builtin_amdgcn_global_load_lds((const unsigned*)((const char*)(gbase) + (voff)[_i]), (LAS unsigned*)(lds + (bufoff) + ldsw + _i * 8192), 16, 0, 0); } while (0)
; #define PG8_LDA(dst, b, h) do { _Pragma("unroll") for (int m = 0; m < 4; ++m) _Pragma("unroll") for (int k = 0; k < 2; ++k) dst[m][k] = *(const LAS bf16x8*)(lds + PG8_SA(b, h) + aoff + m * 2048 + k * 1024); } while (0)
; #define PG8_LDB(dst, b, h) do { _Pragma("unroll") for (int n = 0; n < 2; ++n) _Pragma("unroll") for (int k = 0; k < 2; ++k) dst[n][k] = *(const LAS bf16x8*)(lds + PG8_SB(b, h) + boff + n * 2048 + k * 1024); } while (0)
; #define PG8_MMA(ai, bj, At, Bt) do { __builtin_amdgcn_s_setprio(1); _Pragma("unroll") for (int m = 0; m < 4; ++m) _Pragma("unroll") for (int n = 0; n < 2; ++n) _Pragma("unroll") for (int k = 0; k < 2; ++k) \
;         acc[ai][bj][m][n] = __builtin_amdgcn_mfma_f32_16x16x32_bf16(Bt[n][k], At[m][k], acc[ai][bj][m][n], 0, 0, 0); __builtin_amdgcn_s_setprio(0); } while (0)
; #define PG8_WAIT_V(n) asm volatile("s_waitcnt vmcnt(" #n ")" ::: "memory")
; #define PG8_WAIT_L(n) asm volatile("s_waitcnt lgkmcnt(" #n ")" ::: "memory")
; #define PG8_BAR __builtin_amdgcn_s_barrier()
; #define PG8_SCHED __builtin_amdgcn_sched_barrier(0)
; template <class Epi, class Sched, bool ALIGN_EPI = false, bool SP2 = false>
; __device__ __forceinline__ void gemm_phase(LAS unsigned char* lds, const Gemm g, const Sched& S, const Epi& E) {
;     ...
;             PG8_WAIT_V(8); PG8_WAIT_L(0); PG8_BAR; PG8_MMA(1, 0, At, B0); PG8_MMA(1, 1, At, B1); PG8_BAR; PG8_SCHED;
;             PG8_LDB(B0, 1, 0); PG8_LDB(B1, 1, 1); PG8_SCHED; PG8_LDA(At, 1, 0); PG8_STAGE(PG8_SA(0, 1), a2 + hstep, voffA);
	s_setprio 1
	s_waitcnt lgkmcnt(0)
	v_mfma_f32_16x16x32_bf16 v[60:63], v[142:145], v[184:187], v[60:63]
	v_mfma_f32_16x16x32_bf16 v[56:59], v[160:163], v[184:187], v[56:59]
	v_mfma_f32_16x16x32_bf16 v[44:47], v[142:145], v[198:201], v[44:47]
	v_mfma_f32_16x16x32_bf16 v[40:43], v[160:163], v[198:201], v[40:43]
	v_mfma_f32_16x16x32_bf16 v[28:31], v[142:145], v[206:209], v[28:31]
	v_mfma_f32_16x16x32_bf16 v[24:27], v[160:163], v[206:209], v[24:27]
	v_mfma_f32_16x16x32_bf16 v[12:15], v[142:145], v[214:217], v[12:15]
	v_mfma_f32_16x16x32_bf16 v[8:11], v[160:163], v[214:217], v[8:11]
	v_mfma_f32_16x16x32_bf16 v[60:63], v[156:159], v[188:191], v[60:63]
	v_mfma_f32_16x16x32_bf16 v[56:59], v[164:167], v[188:191], v[56:59]
	v_mfma_f32_16x16x32_bf16 v[44:47], v[156:159], v[202:205], v[44:47]
	v_mfma_f32_16x16x32_bf16 v[40:43], v[164:167], v[202:205], v[40:43]
	v_mfma_f32_16x16x32_bf16 v[28:31], v[156:159], v[210:213], v[28:31]
	v_mfma_f32_16x16x32_bf16 v[24:27], v[164:167], v[210:213], v[24:27]
	v_mfma_f32_16x16x32_bf16 v[12:15], v[156:159], v[228:231], v[12:15]
	v_mfma_f32_16x16x32_bf16 v[8:11], v[164:167], v[228:231], v[8:11]
	s_setprio 0
	s_setprio 1
	v_mfma_f32_16x16x32_bf16 v[52:55], v[168:171], v[184:187], v[52:55]
	v_mfma_f32_16x16x32_bf16 v[48:51], v[176:179], v[184:187], v[48:51]
	v_mfma_f32_16x16x32_bf16 v[36:39], v[168:171], v[198:201], v[36:39]
	v_mfma_f32_16x16x32_bf16 v[32:35], v[176:179], v[198:201], v[32:35]
	v_mfma_f32_16x16x32_bf16 v[20:23], v[168:171], v[206:209], v[20:23]
	v_mfma_f32_16x16x32_bf16 v[16:19], v[176:179], v[206:209], v[16:19]
	v_mfma_f32_16x16x32_bf16 v[4:7], v[168:171], v[214:217], v[4:7]
	v_mfma_f32_16x16x32_bf16 v[0:3], v[176:179], v[214:217], v[0:3]
	v_mfma_f32_16x16x32_bf16 v[52:55], v[172:175], v[188:191], v[52:55]
	v_mfma_f32_16x16x32_bf16 v[48:51], v[180:183], v[188:191], v[48:51]
	v_mfma_f32_16x16x32_bf16 v[36:39], v[172:175], v[202:205], v[36:39]
	v_mfma_f32_16x16x32_bf16 v[32:35], v[180:183], v[202:205], v[32:35]
	v_mfma_f32_16x16x32_bf16 v[20:23], v[172:175], v[210:213], v[20:23]
	v_mfma_f32_16x16x32_bf16 v[16:19], v[180:183], v[210:213], v[16:19]
	v_mfma_f32_16x16x32_bf16 v[4:7], v[172:175], v[228:231], v[4:7]
	v_mfma_f32_16x16x32_bf16 v[0:3], v[180:183], v[228:231], v[0:3]
	s_setprio 0
	s_barrier
	s_add_i32 s44, 0, 0x18000
	s_add_i32 s46, 0, 0x1c000
	v_add_u32_e32 v164, s44, v149
	v_add_u32_e32 v180, s46, v149
	ds_read_b128 v[142:145], v164
	ds_read_b128 v[156:159], v164 offset:1024
	ds_read_b128 v[160:163], v164 offset:2048
	ds_read_b128 v[164:167], v164 offset:3072
	ds_read_b128 v[168:171], v180
	ds_read_b128 v[172:175], v180 offset:1024
	ds_read_b128 v[176:179], v180 offset:2048
	ds_read_b128 v[180:183], v180 offset:3072
	s_mov_b32 m0, s34
	s_nop 0
	global_load_lds_dwordx4 v132, s[14:15]
	s_mov_b32 m0, s35
	s_nop 0
	global_load_lds_dwordx4 v130, s[14:15]
	s_add_u32 s14, s14, 0x100000
	s_addc_u32 s15, s15, 0
	s_mov_b32 m0, s36
	ds_read_b128 v[184:187], v155 offset:32768
	ds_read_b128 v[188:191], v155 offset:33792
	ds_read_b128 v[198:201], v155 offset:34816
	ds_read_b128 v[202:205], v155 offset:35840
	ds_read_b128 v[206:209], v155 offset:36864
	ds_read_b128 v[210:213], v155 offset:37888
	ds_read_b128 v[214:217], v155 offset:38912
	ds_read_b128 v[228:231], v155 offset:39936
	global_load_lds_dwordx4 v132, s[14:15]
	s_mov_b32 m0, s37
	s_nop 0
	global_load_lds_dwordx4 v130, s[14:15]
	s_waitcnt vmcnt(8)
	s_waitcnt lgkmcnt(0)
	s_barrier
; #define PG8_STAGE(bufoff, gbase, voff) do { _Pragma("unroll") for (int _i = 0; _i < 2; ++_i) \
;         __builtin_amdgcn_global_load_lds((const unsigned*)((const char*)(gbase) + (voff)[_i]), (LAS unsigned*)(lds + (bufoff) + ldsw + _i * 8192), 16, 0, 0); } while (0)
; #define PG8_LDA(dst, b, h) do { _Pragma("unroll") for (int m = 0; m < 4; ++m) _Pragma("unroll") for (int k = 0; k < 2; ++k) dst[m][k] = *(const LAS bf16x8*)(lds + PG8_SA(b, h) + aoff + m * 2048 + k * 1024); } while (0)
; #define PG8_MMA(ai, bj, At, Bt) do { __builtin_amdgcn_s_setprio(1); _Pragma("unroll") for (int m = 0; m < 4; ++m) _Pragma("unroll") for (int n = 0; n < 2; ++n) _Pragma("unroll") for (int k = 0; k < 2; ++k) \
;         acc[ai][bj][m][n] = __builtin_amdgcn_mfma_f32_16x16x32_bf16(Bt[n][k], At[m][k], acc[ai][bj][m][n], 0, 0, 0); __builtin_amdgcn_s_setprio(0); } while (0)
; #define PG8_WAIT_V(n) asm volatile("s_waitcnt vmcnt(" #n ")" ::: "memory")
; #define PG8_WAIT_L(n) asm volatile("s_waitcnt lgkmcnt(" #n ")" ::: "memory")
; #define PG8_BAR __builtin_amdgcn_s_barrier()
; #define PG8_SCHED __builtin_amdgcn_sched_barrier(0)
; template <class Epi, class Sched, bool ALIGN_EPI = false, bool SP2 = false>
; __device__ __forceinline__ void gemm_phase(LAS unsigned char* lds, const Gemm g, const Sched& S, const Epi& E) {
;     ...
;             PG8_WAIT_V(8); PG8_WAIT_L(0); PG8_BAR; PG8_MMA(0, 0, At, B0); PG8_MMA(0, 1, At, B1); PG8_BAR; PG8_SCHED;
;             PG8_LDA(At, 1, 1); PG8_STAGE(PG8_SB(1, 0), b3, voffB); PG8_STAGE(PG8_SB(1, 1), b3 + hstep, voffB); PG8_STAGE(PG8_SA(1, 0), a3, voffA);
;             PG8_WAIT_V(8); PG8_WAIT_L(0); PG8_BAR; PG8_MMA(1, 0, At, B0); PG8_MMA(1, 1, At, B1); PG8_BAR; PG8_SCHED;
	s_setprio 1
	s_waitcnt lgkmcnt(0)
	v_mfma_f32_16x16x32_bf16 v[124:127], v[142:145], v[184:187], v[124:127]
	v_mfma_f32_16x16x32_bf16 v[120:123], v[160:163], v[184:187], v[120:123]
	v_mfma_f32_16x16x32_bf16 v[108:111], v[142:145], v[198:201], v[108:111]
	v_mfma_f32_16x16x32_bf16 v[104:107], v[160:163], v[198:201], v[104:107]
	v_mfma_f32_16x16x32_bf16 v[92:95], v[142:145], v[206:209], v[92:95]
	v_mfma_f32_16x16x32_bf16 v[88:91], v[160:163], v[206:209], v[88:91]
	v_mfma_f32_16x16x32_bf16 v[76:79], v[142:145], v[214:217], v[76:79]
	v_mfma_f32_16x16x32_bf16 v[72:75], v[160:163], v[214:217], v[72:75]
	v_mfma_f32_16x16x32_bf16 v[124:127], v[156:159], v[188:191], v[124:127]
	v_mfma_f32_16x16x32_bf16 v[120:123], v[164:167], v[188:191], v[120:123]
	v_mfma_f32_16x16x32_bf16 v[108:111], v[156:159], v[202:205], v[108:111]
	v_mfma_f32_16x16x32_bf16 v[104:107], v[164:167], v[202:205], v[104:107]
	v_mfma_f32_16x16x32_bf16 v[92:95], v[156:159], v[210:213], v[92:95]
	v_mfma_f32_16x16x32_bf16 v[88:91], v[164:167], v[210:213], v[88:91]
	v_mfma_f32_16x16x32_bf16 v[76:79], v[156:159], v[228:231], v[76:79]
	v_mfma_f32_16x16x32_bf16 v[72:75], v[164:167], v[228:231], v[72:75]
	s_setprio 0
	s_setprio 1
	v_mfma_f32_16x16x32_bf16 v[116:119], v[168:171], v[184:187], v[116:119]
	v_mfma_f32_16x16x32_bf16 v[112:115], v[176:179], v[184:187], v[112:115]
	v_mfma_f32_16x16x32_bf16 v[100:103], v[168:171], v[198:201], v[100:103]
	v_mfma_f32_16x16x32_bf16 v[96:99], v[176:179], v[198:201], v[96:99]
	v_mfma_f32_16x16x32_bf16 v[84:87], v[168:171], v[206:209], v[84:87]
	v_mfma_f32_16x16x32_bf16 v[80:83], v[176:179], v[206:209], v[80:83]
	v_mfma_f32_16x16x32_bf16 v[68:71], v[168:171], v[214:217], v[68:71]
	v_mfma_f32_16x16x32_bf16 v[64:67], v[176:179], v[214:217], v[64:67]
	v_mfma_f32_16x16x32_bf16 v[116:119], v[172:175], v[188:191], v[116:119]
	v_mfma_f32_16x16x32_bf16 v[112:115], v[180:183], v[188:191], v[112:115]
	v_mfma_f32_16x16x32_bf16 v[100:103], v[172:175], v[202:205], v[100:103]
	v_mfma_f32_16x16x32_bf16 v[96:99], v[180:183], v[202:205], v[96:99]
	v_mfma_f32_16x16x32_bf16 v[84:87], v[172:175], v[210:213], v[84:87]
	v_mfma_f32_16x16x32_bf16 v[80:83], v[180:183], v[210:213], v[80:83]
	v_mfma_f32_16x16x32_bf16 v[68:71], v[172:175], v[228:231], v[68:71]
	v_mfma_f32_16x16x32_bf16 v[64:67], v[180:183], v[228:231], v[64:67]
	s_setprio 0
	s_barrier
	s_add_i32 s14, s44, s7
	s_mov_b32 m0, s14
	ds_read_b128 v[184:187], v155 offset:49152
	ds_read_b128 v[188:191], v155 offset:50176
	ds_read_b128 v[198:201], v155 offset:51200
	ds_read_b128 v[202:205], v155 offset:52224
	ds_read_b128 v[206:209], v155 offset:53248
	ds_read_b128 v[210:213], v155 offset:54272
	ds_read_b128 v[214:217], v155 offset:55296
	ds_read_b128 v[228:231], v155 offset:56320
	global_load_lds_dwordx4 v196, s[98:99]
	s_add_i32 m0, s14, 0x2000
	s_add_u32 s12, s12, 0x100080
	s_addc_u32 s13, s13, 0
	s_add_i32 s14, s46, s7
	global_load_lds_dwordx4 v128, s[98:99]
	s_mov_b32 m0, s14
	s_nop 0
	global_load_lds_dwordx4 v196, s[12:13]
	s_add_i32 m0, s14, 0x2000
	s_nop 0
	global_load_lds_dwordx4 v128, s[12:13]
	s_waitcnt vmcnt(6)
	s_waitcnt lgkmcnt(0)
	s_barrier
	s_setprio 1
	s_waitcnt lgkmcnt(0)
	v_mfma_f32_16x16x32_bf16 v[60:63], v[142:145], v[184:187], v[60:63]
	v_mfma_f32_16x16x32_bf16 v[56:59], v[160:163], v[184:187], v[56:59]
	v_mfma_f32_16x16x32_bf16 v[44:47], v[142:145], v[198:201], v[44:47]
	v_mfma_f32_16x16x32_bf16 v[40:43], v[160:163], v[198:201], v[40:43]
	v_mfma_f32_16x16x32_bf16 v[28:31], v[142:145], v[206:209], v[28:31]
	v_mfma_f32_16x16x32_bf16 v[24:27], v[160:163], v[206:209], v[24:27]
	v_mfma_f32_16x16x32_bf16 v[12:15], v[142:145], v[214:217], v[12:15]
	v_mfma_f32_16x16x32_bf16 v[8:11], v[160:163], v[214:217], v[8:11]
	v_mfma_f32_16x16x32_bf16 v[60:63], v[156:159], v[188:191], v[60:63]
	v_mfma_f32_16x16x32_bf16 v[56:59], v[164:167], v[188:191], v[56:59]
	v_mfma_f32_16x16x32_bf16 v[44:47], v[156:159], v[202:205], v[44:47]
	v_mfma_f32_16x16x32_bf16 v[40:43], v[164:167], v[202:205], v[40:43]
	v_mfma_f32_16x16x32_bf16 v[28:31], v[156:159], v[210:213], v[28:31]
	v_mfma_f32_16x16x32_bf16 v[24:27], v[164:167], v[210:213], v[24:27]
	v_mfma_f32_16x16x32_bf16 v[12:15], v[156:159], v[228:231], v[12:15]
	v_mfma_f32_16x16x32_bf16 v[8:11], v[164:167], v[228:231], v[8:11]
	s_setprio 0
	s_setprio 1
	v_mfma_f32_16x16x32_bf16 v[52:55], v[168:171], v[184:187], v[52:55]
	v_mfma_f32_16x16x32_bf16 v[48:51], v[176:179], v[184:187], v[48:51]
	v_mfma_f32_16x16x32_bf16 v[36:39], v[168:171], v[198:201], v[36:39]
	v_mfma_f32_16x16x32_bf16 v[32:35], v[176:179], v[198:201], v[32:35]
	v_mfma_f32_16x16x32_bf16 v[20:23], v[168:171], v[206:209], v[20:23]
	v_mfma_f32_16x16x32_bf16 v[16:19], v[176:179], v[206:209], v[16:19]
	v_mfma_f32_16x16x32_bf16 v[4:7], v[168:171], v[214:217], v[4:7]
	v_mfma_f32_16x16x32_bf16 v[0:3], v[176:179], v[214:217], v[0:3]
	v_mfma_f32_16x16x32_bf16 v[52:55], v[172:175], v[188:191], v[52:55]
	v_mfma_f32_16x16x32_bf16 v[48:51], v[180:183], v[188:191], v[48:51]
	v_mfma_f32_16x16x32_bf16 v[36:39], v[172:175], v[202:205], v[36:39]
	v_mfma_f32_16x16x32_bf16 v[32:35], v[180:183], v[202:205], v[32:35]
	v_mfma_f32_16x16x32_bf16 v[20:23], v[172:175], v[210:213], v[20:23]
	v_mfma_f32_16x16x32_bf16 v[16:19], v[180:183], v[210:213], v[16:19]
	v_mfma_f32_16x16x32_bf16 v[4:7], v[172:175], v[228:231], v[4:7]
	v_mfma_f32_16x16x32_bf16 v[0:3], v[180:183], v[228:231], v[0:3]
	s_setprio 0
	s_barrier
	s_add_i32 s42, s42, 2
	s_add_u32 s10, s10, 0x100
	s_addc_u32 s11, s11, 0
	s_add_u32 s25, s25, 0x100
	s_addc_u32 s41, s41, 0
	s_cmp_gt_u32 s42, 61
	s_cbranch_scc0 .LBB0_260
	s_and_b64 vcc, exec, s[20:21]
	s_cbranch_vccz .LBB0_263
	s_barrier

; #define PG8_STAGE(bufoff, gbase, voff) do { _Pragma("unroll") for (int _i = 0; _i < 2; ++_i) \
;         __builtin_amdgcn_global_load_lds((const unsigned*)((const char*)(gbase) + (voff)[_i]), (LAS unsigned*)(lds + (bufoff) + ldsw + _i * 8192), 16, 0, 0); } while (0)
; #define PG8_LDA(dst, b, h) do { _Pragma("unroll") for (int m = 0; m < 4; ++m) _Pragma("unroll") for (int k = 0; k < 2; ++k) dst[m][k] = *(const LAS bf16x8*)(lds + PG8_SA(b, h) + aoff + m * 2048 + k * 1024); } while (0)
; #define PG8_LDB(dst, b, h) do { _Pragma("unroll") for (int n = 0; n < 2; ++n) _Pragma("unroll") for (int k = 0; k < 2; ++k) dst[n][k] = *(const LAS bf16x8*)(lds + PG8_SB(b, h) + boff + n * 2048 + k * 1024); } while (0)
; #define PG8_MMA(ai, bj, At, Bt) do { __builtin_amdgcn_s_setprio(1); _Pragma("unroll") for (int m = 0; m < 4; ++m) _Pragma("unroll") for (int n = 0; n < 2; ++n) _Pragma("unroll") for (int k = 0; k < 2; ++k) \
;         acc[ai][bj][m][n] = __builtin_amdgcn_mfma_f32_16x16x32_bf16(Bt[n][k], At[m][k], acc[ai][bj][m][n], 0, 0, 0); __builtin_amdgcn_s_setprio(0); } while (0)
; #define PG8_WAIT_V(n) asm volatile("s_waitcnt vmcnt(" #n ")" ::: "memory")
; #define PG8_WAIT_L(n) asm volatile("s_waitcnt lgkmcnt(" #n ")" ::: "memory")
; #define PG8_BAR __builtin_amdgcn_s_barrier()
; #define PG8_SCHED __builtin_amdgcn_sched_barrier(0)
; template <class Epi, class Sched, bool ALIGN_EPI = false, bool SP2 = false>
; __device__ __forceinline__ void gemm_phase(LAS unsigned char* lds, const Gemm g, const Sched& S, const Epi& E) {
;     ...
;             PG8_LDB(B0, 0, 0); PG8_LDB(B1, 0, 1); PG8_SCHED; PG8_LDA(At, 0, 0); PG8_STAGE(PG8_SA(1, 1), a1 + hstep, voffA);
;             PG8_WAIT_V(8); PG8_WAIT_L(0); PG8_BAR; PG8_MMA(0, 0, At, B0); PG8_MMA(0, 1, At, B1); PG8_BAR; PG8_SCHED;
;             PG8_LDA(At, 0, 1); PG8_STAGE(PG8_SB(0, 0), b2, voffB); PG8_STAGE(PG8_SB(0, 1), b2 + hstep, voffB); PG8_STAGE(PG8_SA(0, 0), a2, voffA);
.LBB0_424:
	s_add_u32 s100, s10, 0xfff00000
	s_addc_u32 s101, s11, -1
	s_add_u32 s12, s10, 0xfff00080
	s_addc_u32 s13, s11, -1
	s_add_i32 s48, 0, 0x10000
	s_cmp_eq_u32 s42, 60
	s_cselect_b32 s15, s2, s13
	s_cselect_b32 s14, s3, s12
	v_add_u32_e32 v146, s48, v149
	s_cselect_b32 s13, s17, s41
	s_cselect_b32 s12, s23, s25
	s_add_i32 s90, 0, 0x14000
	ds_read_b128 v[142:145], v146
	ds_read_b128 v[156:159], v146 offset:1024
	ds_read_b128 v[160:163], v146 offset:2048
	ds_read_b128 v[164:167], v146 offset:3072
	v_add_u32_e32 v146, s90, v149
	ds_read_b128 v[168:171], v146
	ds_read_b128 v[172:175], v146 offset:1024
	ds_read_b128 v[176:179], v146 offset:2048
	ds_read_b128 v[180:183], v146 offset:3072
	s_add_i32 m0, s34, 0xc000
	ds_read_b128 v[184:187], v155
	ds_read_b128 v[188:191], v155 offset:1024
	ds_read_b128 v[198:201], v155 offset:2048
	ds_read_b128 v[202:205], v155 offset:3072
	ds_read_b128 v[206:209], v155 offset:4096
	ds_read_b128 v[210:213], v155 offset:5120
	ds_read_b128 v[214:217], v155 offset:6144
	ds_read_b128 v[228:231], v155 offset:7168
	s_mov_b32 m0, s38
	s_nop 0
	global_load_lds_dwordx4 v128, s[100:101]
	s_mov_b32 m0, s39
	s_nop 0
	global_load_lds_dwordx4 v130, s[100:101]
	s_add_i32 m0, s34, 0xc000
	s_nop 0
	global_load_lds_dwordx4 v138, s[10:11]
	s_add_i32 m0, s34, 0xe000
	s_nop 0
	global_load_lds_dwordx4 v140, s[10:11]
	s_waitcnt vmcnt(8)
	s_waitcnt lgkmcnt(0)
	s_barrier
	s_setprio 1
	s_waitcnt lgkmcnt(0)
	v_mfma_f32_16x16x32_bf16 v[124:127], v[142:145], v[184:187], v[124:127]
	v_mfma_f32_16x16x32_bf16 v[120:123], v[160:163], v[184:187], v[120:123]
	v_mfma_f32_16x16x32_bf16 v[108:111], v[142:145], v[198:201], v[108:111]
	v_mfma_f32_16x16x32_bf16 v[104:107], v[160:163], v[198:201], v[104:107]
	v_mfma_f32_16x16x32_bf16 v[92:95], v[142:145], v[206:209], v[92:95]
	v_mfma_f32_16x16x32_bf16 v[88:91], v[160:163], v[206:209], v[88:91]
	v_mfma_f32_16x16x32_bf16 v[76:79], v[142:145], v[214:217], v[76:79]
	v_mfma_f32_16x16x32_bf16 v[72:75], v[160:163], v[214:217], v[72:75]
	v_mfma_f32_16x16x32_bf16 v[124:127], v[156:159], v[188:191], v[124:127]
	v_mfma_f32_16x16x32_bf16 v[120:123], v[164:167], v[188:191], v[120:123]
	v_mfma_f32_16x16x32_bf16 v[108:111], v[156:159], v[202:205], v[108:111]
	v_mfma_f32_16x16x32_bf16 v[104:107], v[164:167], v[202:205], v[104:107]
	v_mfma_f32_16x16x32_bf16 v[92:95], v[156:159], v[210:213], v[92:95]
	v_mfma_f32_16x16x32_bf16 v[88:91], v[164:167], v[210:213], v[88:91]
	v_mfma_f32_16x16x32_bf16 v[76:79], v[156:159], v[228:231], v[76:79]
	v_mfma_f32_16x16x32_bf16 v[72:75], v[164:167], v[228:231], v[72:75]
	s_setprio 0
	s_setprio 1
	v_mfma_f32_16x16x32_bf16 v[116:119], v[168:171], v[184:187], v[116:119]
	v_mfma_f32_16x16x32_bf16 v[112:115], v[176:179], v[184:187], v[112:115]
	v_mfma_f32_16x16x32_bf16 v[100:103], v[168:171], v[198:201], v[100:103]
	v_mfma_f32_16x16x32_bf16 v[96:99], v[176:179], v[198:201], v[96:99]
	v_mfma_f32_16x16x32_bf16 v[84:87], v[168:171], v[206:209], v[84:87]
	v_mfma_f32_16x16x32_bf16 v[80:83], v[176:179], v[206:209], v[80:83]
	v_mfma_f32_16x16x32_bf16 v[68:71], v[168:171], v[214:217], v[68:71]
	v_mfma_f32_16x16x32_bf16 v[64:67], v[176:179], v[214:217], v[64:67]
	v_mfma_f32_16x16x32_bf16 v[116:119], v[172:175], v[188:191], v[116:119]
	v_mfma_f32_16x16x32_bf16 v[112:115], v[180:183], v[188:191], v[112:115]
	v_mfma_f32_16x16x32_bf16 v[100:103], v[172:175], v[202:205], v[100:103]
	v_mfma_f32_16x16x32_bf16 v[96:99], v[180:183], v[202:205], v[96:99]
	v_mfma_f32_16x16x32_bf16 v[84:87], v[172:175], v[210:213], v[84:87]
	v_mfma_f32_16x16x32_bf16 v[80:83], v[180:183], v[210:213], v[80:83]
	v_mfma_f32_16x16x32_bf16 v[68:71], v[172:175], v[228:231], v[68:71]
	v_mfma_f32_16x16x32_bf16 v[64:67], v[180:183], v[228:231], v[64:67]
	s_setprio 0
	s_barrier
	s_add_u32 s98, s12, 0x80
	s_addc_u32 s99, s13, 0
	s_add_i32 s44, s48, s7
	s_mov_b32 m0, s44
	ds_read_b128 v[184:187], v155 offset:16384
	ds_read_b128 v[188:191], v155 offset:17408
	ds_read_b128 v[198:201], v155 offset:18432
	ds_read_b128 v[202:205], v155 offset:19456
	ds_read_b128 v[206:209], v155 offset:20480
	ds_read_b128 v[210:213], v155 offset:21504
	ds_read_b128 v[214:217], v155 offset:22528
	ds_read_b128 v[228:231], v155 offset:23552
	global_load_lds_dwordx4 v196, s[12:13]
	s_add_i32 m0, s44, 0x2000
	s_add_u32 s46, s12, 0x100000
	s_addc_u32 s47, s13, 0
	s_add_i32 s44, s90, s7
	global_load_lds_dwordx4 v132, s[12:13]
	s_mov_b32 m0, s44
	s_nop 0
	global_load_lds_dwordx4 v196, s[46:47]
	s_add_i32 m0, s44, 0x2000
	s_nop 0
	global_load_lds_dwordx4 v132, s[46:47]
	s_waitcnt vmcnt(6)
	s_waitcnt lgkmcnt(0)
	s_barrier
; #define PG8_STAGE(bufoff, gbase, voff) do { _Pragma("unroll") for (int _i = 0; _i < 2; ++_i) \
;         __builtin_amdgcn_global_load_lds((const unsigned*)((const char*)(gbase) + (voff)[_i]), (LAS unsigned*)(lds + (bufoff) + ldsw + _i * 8192), 16, 0, 0); } while (0)
; #define PG8_LDA(dst, b, h) do { _Pragma("unroll") for (int m = 0; m < 4; ++m) _Pragma("unroll") for (int k = 0; k < 2; ++k) dst[m][k] = *(const LAS bf16x8*)(lds + PG8_SA(b, h) + aoff + m * 2048 + k * 1024); } while (0)
; #define PG8_LDB(dst, b, h) do { _Pragma("unroll") for (int n = 0; n < 2; ++n) _Pragma("unroll") for (int k = 0; k < 2; ++k) dst[n][k] = *(const LAS bf16x8*)(lds + PG8_SB(b, h) + boff + n * 2048 + k * 1024); } while (0)
; #define PG8_MMA(ai, bj, At, Bt) do { __builtin_amdgcn_s_setprio(1); _Pragma("unroll") for (int m = 0; m < 4; ++m) _Pragma("unroll") for (int n = 0; n < 2; ++n) _Pragma("unroll") for (int k = 0; k < 2; ++k) \
;         acc[ai][bj][m][n] = __builtin_amdgcn_mfma_f32_16x16x32_bf16(Bt[n][k], At[m][k], acc[ai][bj][m][n], 0, 0, 0); __builtin_amdgcn_s_setprio(0); } while (0)
; #define PG8_WAIT_V(n) asm volatile("s_waitcnt vmcnt(" #n ")" ::: "memory")
; #define PG8_WAIT_L(n) asm volatile("s_waitcnt lgkmcnt(" #n ")" ::: "memory")
; #define PG8_BAR __builtin_amdgcn_s_barrier()
; #define PG8_SCHED __builtin_amdgcn_sched_barrier(0)
; template <class Epi, class Sched, bool ALIGN_EPI = false, bool SP2 = false>
; __device__ __forceinline__ void gemm_phase(LAS unsigned char* lds, const Gemm g, const Sched& S, const Epi& E) {
;     ...
;             PG8_WAIT_V(8); PG8_WAIT_L(0); PG8_BAR; PG8_MMA(1, 0, At, B0); PG8_MMA(1, 1, At, B1); PG8_BAR; PG8_SCHED;
;             PG8_LDB(B0, 1, 0); PG8_LDB(B1, 1, 1); PG8_SCHED; PG8_LDA(At, 1, 0); PG8_STAGE(PG8_SA(0, 1), a2 + hstep, voffA);
	s_setprio 1
	s_waitcnt lgkmcnt(0)
	v_mfma_f32_16x16x32_bf16 v[60:63], v[142:145], v[184:187], v[60:63]
	v_mfma_f32_16x16x32_bf16 v[56:59], v[160:163], v[184:187], v[56:59]
	v_mfma_f32_16x16x32_bf16 v[44:47], v[142:145], v[198:201], v[44:47]
	v_mfma_f32_16x16x32_bf16 v[40:43], v[160:163], v[198:201], v[40:43]
	v_mfma_f32_16x16x32_bf16 v[28:31], v[142:145], v[206:209], v[28:31]
	v_mfma_f32_16x16x32_bf16 v[24:27], v[160:163], v[206:209], v[24:27]
	v_mfma_f32_16x16x32_bf16 v[12:15], v[142:145], v[214:217], v[12:15]
	v_mfma_f32_16x16x32_bf16 v[8:11], v[160:163], v[214:217], v[8:11]
	v_mfma_f32_16x16x32_bf16 v[60:63], v[156:159], v[188:191], v[60:63]
	v_mfma_f32_16x16x32_bf16 v[56:59], v[164:167], v[188:191], v[56:59]
	v_mfma_f32_16x16x32_bf16 v[44:47], v[156:159], v[202:205], v[44:47]
	v_mfma_f32_16x16x32_bf16 v[40:43], v[164:167], v[202:205], v[40:43]
	v_mfma_f32_16x16x32_bf16 v[28:31], v[156:159], v[210:213], v[28:31]
	v_mfma_f32_16x16x32_bf16 v[24:27], v[164:167], v[210:213], v[24:27]
	v_mfma_f32_16x16x32_bf16 v[12:15], v[156:159], v[228:231], v[12:15]
	v_mfma_f32_16x16x32_bf16 v[8:11], v[164:167], v[228:231], v[8:11]
	s_setprio 0
	s_setprio 1
	v_mfma_f32_16x16x32_bf16 v[52:55], v[168:171], v[184:187], v[52:55]
	v_mfma_f32_16x16x32_bf16 v[48:51], v[176:179], v[184:187], v[48:51]
	v_mfma_f32_16x16x32_bf16 v[36:39], v[168:171], v[198:201], v[36:39]
	v_mfma_f32_16x16x32_bf16 v[32:35], v[176:179], v[198:201], v[32:35]
	v_mfma_f32_16x16x32_bf16 v[20:23], v[168:171], v[206:209], v[20:23]
	v_mfma_f32_16x16x32_bf16 v[16:19], v[176:179], v[206:209], v[16:19]
	v_mfma_f32_16x16x32_bf16 v[4:7], v[168:171], v[214:217], v[4:7]
	v_mfma_f32_16x16x32_bf16 v[0:3], v[176:179], v[214:217], v[0:3]
	v_mfma_f32_16x16x32_bf16 v[52:55], v[172:175], v[188:191], v[52:55]
	v_mfma_f32_16x16x32_bf16 v[48:51], v[180:183], v[188:191], v[48:51]
	v_mfma_f32_16x16x32_bf16 v[36:39], v[172:175], v[202:205], v[36:39]
	v_mfma_f32_16x16x32_bf16 v[32:35], v[180:183], v[202:205], v[32:35]
	v_mfma_f32_16x16x32_bf16 v[20:23], v[172:175], v[210:213], v[20:23]
	v_mfma_f32_16x16x32_bf16 v[16:19], v[180:183], v[210:213], v[16:19]
	v_mfma_f32_16x16x32_bf16 v[4:7], v[172:175], v[228:231], v[4:7]
	v_mfma_f32_16x16x32_bf16 v[0:3], v[180:183], v[228:231], v[0:3]
	s_setprio 0
	s_barrier
	s_add_i32 s91, 0, 0x18000
	s_add_i32 s58, 0, 0x1c000
	v_add_u32_e32 v164, s91, v149
	v_add_u32_e32 v180, s58, v149
	ds_read_b128 v[142:145], v164
	ds_read_b128 v[156:159], v164 offset:1024
	ds_read_b128 v[160:163], v164 offset:2048
	ds_read_b128 v[164:167], v164 offset:3072
	ds_read_b128 v[168:171], v180
	ds_read_b128 v[172:175], v180 offset:1024
	ds_read_b128 v[176:179], v180 offset:2048
	ds_read_b128 v[180:183], v180 offset:3072
	s_mov_b32 m0, s34
	s_nop 0
	global_load_lds_dwordx4 v128, s[14:15]
	s_mov_b32 m0, s35
	s_nop 0
	global_load_lds_dwordx4 v130, s[14:15]
	s_add_u32 s14, s14, 0x100000
	s_addc_u32 s15, s15, 0
	s_mov_b32 m0, s36
	ds_read_b128 v[184:187], v155 offset:32768
	ds_read_b128 v[188:191], v155 offset:33792
	ds_read_b128 v[198:201], v155 offset:34816
	ds_read_b128 v[202:205], v155 offset:35840
	ds_read_b128 v[206:209], v155 offset:36864
	ds_read_b128 v[210:213], v155 offset:37888
	ds_read_b128 v[214:217], v155 offset:38912
	ds_read_b128 v[228:231], v155 offset:39936
	global_load_lds_dwordx4 v128, s[14:15]
	s_mov_b32 m0, s37
	s_nop 0
	global_load_lds_dwordx4 v130, s[14:15]
	s_waitcnt vmcnt(8)
	s_waitcnt lgkmcnt(0)
	s_barrier
; #define PG8_STAGE(bufoff, gbase, voff) do { _Pragma("unroll") for (int _i = 0; _i < 2; ++_i) \
;         __builtin_amdgcn_global_load_lds((const unsigned*)((const char*)(gbase) + (voff)[_i]), (LAS unsigned*)(lds + (bufoff) + ldsw + _i * 8192), 16, 0, 0); } while (0)
; #define PG8_LDA(dst, b, h) do { _Pragma("unroll") for (int m = 0; m < 4; ++m) _Pragma("unroll") for (int k = 0; k < 2; ++k) dst[m][k] = *(const LAS bf16x8*)(lds + PG8_SA(b, h) + aoff + m * 2048 + k * 1024); } while (0)
; #define PG8_MMA(ai, bj, At, Bt) do { __builtin_amdgcn_s_setprio(1); _Pragma("unroll") for (int m = 0; m < 4; ++m) _Pragma("unroll") for (int n = 0; n < 2; ++n) _Pragma("unroll") for (int k = 0; k < 2; ++k) \
;         acc[ai][bj][m][n] = __builtin_amdgcn_mfma_f32_16x16x32_bf16(Bt[n][k], At[m][k], acc[ai][bj][m][n], 0, 0, 0); __builtin_amdgcn_s_setprio(0); } while (0)
; #define PG8_WAIT_V(n) asm volatile("s_waitcnt vmcnt(" #n ")" ::: "memory")
; #define PG8_WAIT_L(n) asm volatile("s_waitcnt lgkmcnt(" #n ")" ::: "memory")
; #define PG8_BAR __builtin_amdgcn_s_barrier()
; #define PG8_SCHED __builtin_amdgcn_sched_barrier(0)
; template <class Epi, class Sched, bool ALIGN_EPI = false, bool SP2 = false>
; __device__ __forceinline__ void gemm_phase(LAS unsigned char* lds, const Gemm g, const Sched& S, const Epi& E) {
;     ...
;             PG8_WAIT_V(8); PG8_WAIT_L(0); PG8_BAR; PG8_MMA(0, 0, At, B0); PG8_MMA(0, 1, At, B1); PG8_BAR; PG8_SCHED;
;             PG8_LDA(At, 1, 1); PG8_STAGE(PG8_SB(1, 0), b3, voffB); PG8_STAGE(PG8_SB(1, 1), b3 + hstep, voffB); PG8_STAGE(PG8_SA(1, 0), a3, voffA);
;             PG8_WAIT_V(8); PG8_WAIT_L(0); PG8_BAR; PG8_MMA(1, 0, At, B0); PG8_MMA(1, 1, At, B1); PG8_BAR; PG8_SCHED;
	s_setprio 1
	s_waitcnt lgkmcnt(0)
	v_mfma_f32_16x16x32_bf16 v[124:127], v[142:145], v[184:187], v[124:127]
	v_mfma_f32_16x16x32_bf16 v[120:123], v[160:163], v[184:187], v[120:123]
	v_mfma_f32_16x16x32_bf16 v[108:111], v[142:145], v[198:201], v[108:111]
	v_mfma_f32_16x16x32_bf16 v[104:107], v[160:163], v[198:201], v[104:107]
	v_mfma_f32_16x16x32_bf16 v[92:95], v[142:145], v[206:209], v[92:95]
	v_mfma_f32_16x16x32_bf16 v[88:91], v[160:163], v[206:209], v[88:91]
	v_mfma_f32_16x16x32_bf16 v[76:79], v[142:145], v[214:217], v[76:79]
	v_mfma_f32_16x16x32_bf16 v[72:75], v[160:163], v[214:217], v[72:75]
	v_mfma_f32_16x16x32_bf16 v[124:127], v[156:159], v[188:191], v[124:127]
	v_mfma_f32_16x16x32_bf16 v[120:123], v[164:167], v[188:191], v[120:123]
	v_mfma_f32_16x16x32_bf16 v[108:111], v[156:159], v[202:205], v[108:111]
	v_mfma_f32_16x16x32_bf16 v[104:107], v[164:167], v[202:205], v[104:107]
	v_mfma_f32_16x16x32_bf16 v[92:95], v[156:159], v[210:213], v[92:95]
	v_mfma_f32_16x16x32_bf16 v[88:91], v[164:167], v[210:213], v[88:91]
	v_mfma_f32_16x16x32_bf16 v[76:79], v[156:159], v[228:231], v[76:79]
	v_mfma_f32_16x16x32_bf16 v[72:75], v[164:167], v[228:231], v[72:75]
	s_setprio 0
	s_setprio 1
	v_mfma_f32_16x16x32_bf16 v[116:119], v[168:171], v[184:187], v[116:119]
	v_mfma_f32_16x16x32_bf16 v[112:115], v[176:179], v[184:187], v[112:115]
	v_mfma_f32_16x16x32_bf16 v[100:103], v[168:171], v[198:201], v[100:103]
	v_mfma_f32_16x16x32_bf16 v[96:99], v[176:179], v[198:201], v[96:99]
	v_mfma_f32_16x16x32_bf16 v[84:87], v[168:171], v[206:209], v[84:87]
	v_mfma_f32_16x16x32_bf16 v[80:83], v[176:179], v[206:209], v[80:83]
	v_mfma_f32_16x16x32_bf16 v[68:71], v[168:171], v[214:217], v[68:71]
	v_mfma_f32_16x16x32_bf16 v[64:67], v[176:179], v[214:217], v[64:67]
	v_mfma_f32_16x16x32_bf16 v[116:119], v[172:175], v[188:191], v[116:119]
	v_mfma_f32_16x16x32_bf16 v[112:115], v[180:183], v[188:191], v[112:115]
	v_mfma_f32_16x16x32_bf16 v[100:103], v[172:175], v[202:205], v[100:103]
	v_mfma_f32_16x16x32_bf16 v[96:99], v[180:183], v[202:205], v[96:99]
	v_mfma_f32_16x16x32_bf16 v[84:87], v[172:175], v[210:213], v[84:87]
	v_mfma_f32_16x16x32_bf16 v[80:83], v[180:183], v[210:213], v[80:83]
	v_mfma_f32_16x16x32_bf16 v[68:71], v[172:175], v[228:231], v[68:71]
	v_mfma_f32_16x16x32_bf16 v[64:67], v[180:183], v[228:231], v[64:67]
	s_setprio 0
	s_barrier
	s_add_i32 s14, s91, s7
	s_mov_b32 m0, s14
	ds_read_b128 v[184:187], v155 offset:49152
	ds_read_b128 v[188:191], v155 offset:50176
	ds_read_b128 v[198:201], v155 offset:51200
	ds_read_b128 v[202:205], v155 offset:52224
	ds_read_b128 v[206:209], v155 offset:53248
	ds_read_b128 v[210:213], v155 offset:54272
	ds_read_b128 v[214:217], v155 offset:55296
	ds_read_b128 v[228:231], v155 offset:56320
	global_load_lds_dwordx4 v196, s[98:99]
	s_add_i32 m0, s14, 0x2000
	s_add_u32 s12, s12, 0x100080
	s_addc_u32 s13, s13, 0
	s_add_i32 s14, s58, s7
	global_load_lds_dwordx4 v132, s[98:99]
	s_mov_b32 m0, s14
	s_nop 0
	global_load_lds_dwordx4 v196, s[12:13]
	s_add_i32 m0, s14, 0x2000
	s_nop 0
	global_load_lds_dwordx4 v132, s[12:13]
	s_waitcnt vmcnt(6)
	s_waitcnt lgkmcnt(0)
	s_barrier
	s_setprio 1
	s_waitcnt lgkmcnt(0)
	v_mfma_f32_16x16x32_bf16 v[60:63], v[142:145], v[184:187], v[60:63]
	v_mfma_f32_16x16x32_bf16 v[56:59], v[160:163], v[184:187], v[56:59]
	v_mfma_f32_16x16x32_bf16 v[44:47], v[142:145], v[198:201], v[44:47]
	v_mfma_f32_16x16x32_bf16 v[40:43], v[160:163], v[198:201], v[40:43]
	v_mfma_f32_16x16x32_bf16 v[28:31], v[142:145], v[206:209], v[28:31]
	v_mfma_f32_16x16x32_bf16 v[24:27], v[160:163], v[206:209], v[24:27]
	v_mfma_f32_16x16x32_bf16 v[12:15], v[142:145], v[214:217], v[12:15]
	v_mfma_f32_16x16x32_bf16 v[8:11], v[160:163], v[214:217], v[8:11]
	v_mfma_f32_16x16x32_bf16 v[60:63], v[156:159], v[188:191], v[60:63]
	v_mfma_f32_16x16x32_bf16 v[56:59], v[164:167], v[188:191], v[56:59]
	v_mfma_f32_16x16x32_bf16 v[44:47], v[156:159], v[202:205], v[44:47]
	v_mfma_f32_16x16x32_bf16 v[40:43], v[164:167], v[202:205], v[40:43]
	v_mfma_f32_16x16x32_bf16 v[28:31], v[156:159], v[210:213], v[28:31]
	v_mfma_f32_16x16x32_bf16 v[24:27], v[164:167], v[210:213], v[24:27]
	v_mfma_f32_16x16x32_bf16 v[12:15], v[156:159], v[228:231], v[12:15]
	v_mfma_f32_16x16x32_bf16 v[8:11], v[164:167], v[228:231], v[8:11]
	s_setprio 0
	s_setprio 1
	v_mfma_f32_16x16x32_bf16 v[52:55], v[168:171], v[184:187], v[52:55]
	v_mfma_f32_16x16x32_bf16 v[48:51], v[176:179], v[184:187], v[48:51]
	v_mfma_f32_16x16x32_bf16 v[36:39], v[168:171], v[198:201], v[36:39]
	v_mfma_f32_16x16x32_bf16 v[32:35], v[176:179], v[198:201], v[32:35]
	v_mfma_f32_16x16x32_bf16 v[20:23], v[168:171], v[206:209], v[20:23]
	v_mfma_f32_16x16x32_bf16 v[16:19], v[176:179], v[206:209], v[16:19]
	v_mfma_f32_16x16x32_bf16 v[4:7], v[168:171], v[214:217], v[4:7]
	v_mfma_f32_16x16x32_bf16 v[0:3], v[176:179], v[214:217], v[0:3]
	v_mfma_f32_16x16x32_bf16 v[52:55], v[172:175], v[188:191], v[52:55]
	v_mfma_f32_16x16x32_bf16 v[48:51], v[180:183], v[188:191], v[48:51]
	v_mfma_f32_16x16x32_bf16 v[36:39], v[172:175], v[202:205], v[36:39]
	v_mfma_f32_16x16x32_bf16 v[32:35], v[180:183], v[202:205], v[32:35]
	v_mfma_f32_16x16x32_bf16 v[20:23], v[172:175], v[210:213], v[20:23]
	v_mfma_f32_16x16x32_bf16 v[16:19], v[180:183], v[210:213], v[16:19]
	v_mfma_f32_16x16x32_bf16 v[4:7], v[172:175], v[228:231], v[4:7]
	v_mfma_f32_16x16x32_bf16 v[0:3], v[180:183], v[228:231], v[0:3]
	s_setprio 0
	s_barrier
	s_add_i32 s42, s42, 2
	s_add_u32 s10, s10, 0x100
	s_addc_u32 s11, s11, 0
	s_add_u32 s25, s25, 0x100
	s_addc_u32 s41, s41, 0
	s_cmp_gt_u32 s42, 61
	s_cbranch_scc0 .LBB0_424
	s_and_b64 vcc, exec, s[20:21]
	s_cbranch_vccz .LBB0_427
	s_barrier

; #define PG8_STAGE(bufoff, gbase, voff) do { _Pragma("unroll") for (int _i = 0; _i < 2; ++_i) \
;         __builtin_amdgcn_global_load_lds((const unsigned*)((const char*)(gbase) + (voff)[_i]), (LAS unsigned*)(lds + (bufoff) + ldsw + _i * 8192), 16, 0, 0); } while (0)
; #define PG8_LDA(dst, b, h) do { _Pragma("unroll") for (int m = 0; m < 4; ++m) _Pragma("unroll") for (int k = 0; k < 2; ++k) dst[m][k] = *(const LAS bf16x8*)(lds + PG8_SA(b, h) + aoff + m * 2048 + k * 1024); } while (0)
; #define PG8_LDB(dst, b, h) do { _Pragma("unroll") for (int n = 0; n < 2; ++n) _Pragma("unroll") for (int k = 0; k < 2; ++k) dst[n][k] = *(const LAS bf16x8*)(lds + PG8_SB(b, h) + boff + n * 2048 + k * 1024); } while (0)
; #define PG8_MMA(ai, bj, At, Bt) do { __builtin_amdgcn_s_setprio(1); _Pragma("unroll") for (int m = 0; m < 4; ++m) _Pragma("unroll") for (int n = 0; n < 2; ++n) _Pragma("unroll") for (int k = 0; k < 2; ++k) \
;         acc[ai][bj][m][n] = __builtin_amdgcn_mfma_f32_16x16x32_bf16(Bt[n][k], At[m][k], acc[ai][bj][m][n], 0, 0, 0); __builtin_amdgcn_s_setprio(0); } while (0)
; #define PG8_WAIT_V(n) asm volatile("s_waitcnt vmcnt(" #n ")" ::: "memory")
; #define PG8_WAIT_L(n) asm volatile("s_waitcnt lgkmcnt(" #n ")" ::: "memory")
; #define PG8_BAR __builtin_amdgcn_s_barrier()
; #define PG8_SCHED __builtin_amdgcn_sched_barrier(0)
; template <class Epi, class Sched, bool ALIGN_EPI = false, bool SP2 = false>
; __device__ __forceinline__ void gemm_phase(LAS unsigned char* lds, const Gemm g, const Sched& S, const Epi& E) {
;     ...
;             PG8_LDB(B0, 0, 0); PG8_LDB(B1, 0, 1); PG8_SCHED; PG8_LDA(At, 0, 0); PG8_STAGE(PG8_SA(1, 1), a1 + hstep, voffA);
;             PG8_WAIT_V(8); PG8_WAIT_L(0); PG8_BAR; PG8_MMA(0, 0, At, B0); PG8_MMA(0, 1, At, B1); PG8_BAR; PG8_SCHED;
;             PG8_LDA(At, 0, 1); PG8_STAGE(PG8_SB(0, 0), b2, voffB); PG8_STAGE(PG8_SB(0, 1), b2 + hstep, voffB); PG8_STAGE(PG8_SA(0, 0), a2, voffA);
.LBB0_510:
	v_add_u32_e32 v138, s48, v141
	ds_read_b128 v[144:147], v138
	ds_read_b128 v[148:151], v138 offset:1024
	ds_read_b128 v[152:155], v138 offset:2048
	ds_read_b128 v[156:159], v138 offset:3072
	v_add_u32_e32 v138, s90, v141
	ds_read_b128 v[160:163], v138
	ds_read_b128 v[164:167], v138 offset:1024
	ds_read_b128 v[168:171], v138 offset:2048
	ds_read_b128 v[172:175], v138 offset:3072
	s_add_u32 s100, s24, 0xfff00000
	s_addc_u32 s101, s25, -1
	s_add_u32 s26, s24, 0xfff00080
	s_addc_u32 s27, s25, -1
	s_cmp_eq_u32 s41, 60
	s_cselect_b32 s29, s19, s27
	s_cselect_b32 s28, s37, s26
	s_cselect_b32 s27, s15, s40
	s_cselect_b32 s26, s38, s39
	s_add_i32 m0, s3, 0xc000
	ds_read_b128 v[176:179], v143
	ds_read_b128 v[180:183], v143 offset:1024
	ds_read_b128 v[184:187], v143 offset:2048
	ds_read_b128 v[188:191], v143 offset:3072
	ds_read_b128 v[198:201], v143 offset:4096
	ds_read_b128 v[202:205], v143 offset:5120
	ds_read_b128 v[206:209], v143 offset:6144
	ds_read_b128 v[210:213], v143 offset:7168
	s_mov_b32 m0, s30
	s_nop 0
	global_load_lds_dwordx4 v132, s[100:101]
	s_mov_b32 m0, s31
	s_nop 0
	global_load_lds_dwordx4 v130, s[100:101]
	s_add_i32 m0, s3, 0xc000
	s_nop 0
	global_load_lds_dwordx4 v134, s[24:25]
	s_add_i32 m0, s3, 0xe000
	s_nop 0
	global_load_lds_dwordx4 v136, s[24:25]
	s_waitcnt vmcnt(8)
	s_waitcnt lgkmcnt(0)
	s_barrier
	s_setprio 1
	s_waitcnt lgkmcnt(0)
	v_mfma_f32_16x16x32_bf16 v[124:127], v[144:147], v[176:179], v[124:127]
	v_mfma_f32_16x16x32_bf16 v[120:123], v[152:155], v[176:179], v[120:123]
	v_mfma_f32_16x16x32_bf16 v[116:119], v[144:147], v[184:187], v[116:119]
	v_mfma_f32_16x16x32_bf16 v[108:111], v[152:155], v[184:187], v[108:111]
	v_mfma_f32_16x16x32_bf16 v[100:103], v[144:147], v[198:201], v[100:103]
	v_mfma_f32_16x16x32_bf16 v[92:95], v[152:155], v[198:201], v[92:95]
	v_mfma_f32_16x16x32_bf16 v[80:83], v[144:147], v[206:209], v[80:83]
	v_mfma_f32_16x16x32_bf16 v[72:75], v[152:155], v[206:209], v[72:75]
	v_mfma_f32_16x16x32_bf16 v[124:127], v[148:151], v[180:183], v[124:127]
	v_mfma_f32_16x16x32_bf16 v[120:123], v[156:159], v[180:183], v[120:123]
	v_mfma_f32_16x16x32_bf16 v[116:119], v[148:151], v[188:191], v[116:119]
	v_mfma_f32_16x16x32_bf16 v[108:111], v[156:159], v[188:191], v[108:111]
	v_mfma_f32_16x16x32_bf16 v[100:103], v[148:151], v[202:205], v[100:103]
	v_mfma_f32_16x16x32_bf16 v[92:95], v[156:159], v[202:205], v[92:95]
	v_mfma_f32_16x16x32_bf16 v[80:83], v[148:151], v[210:213], v[80:83]
	v_mfma_f32_16x16x32_bf16 v[72:75], v[156:159], v[210:213], v[72:75]
	s_setprio 0
	s_setprio 1
	v_mfma_f32_16x16x32_bf16 v[112:115], v[160:163], v[176:179], v[112:115]
	v_mfma_f32_16x16x32_bf16 v[104:107], v[168:171], v[176:179], v[104:107]
	v_mfma_f32_16x16x32_bf16 v[96:99], v[160:163], v[184:187], v[96:99]
	v_mfma_f32_16x16x32_bf16 v[88:91], v[168:171], v[184:187], v[88:91]
	v_mfma_f32_16x16x32_bf16 v[84:87], v[160:163], v[198:201], v[84:87]
	v_mfma_f32_16x16x32_bf16 v[76:79], v[168:171], v[198:201], v[76:79]
	v_mfma_f32_16x16x32_bf16 v[68:71], v[160:163], v[206:209], v[68:71]
	v_mfma_f32_16x16x32_bf16 v[64:67], v[168:171], v[206:209], v[64:67]
	v_mfma_f32_16x16x32_bf16 v[112:115], v[164:167], v[180:183], v[112:115]
	v_mfma_f32_16x16x32_bf16 v[104:107], v[172:175], v[180:183], v[104:107]
	v_mfma_f32_16x16x32_bf16 v[96:99], v[164:167], v[188:191], v[96:99]
	v_mfma_f32_16x16x32_bf16 v[88:91], v[172:175], v[188:191], v[88:91]
	v_mfma_f32_16x16x32_bf16 v[84:87], v[164:167], v[202:205], v[84:87]
	v_mfma_f32_16x16x32_bf16 v[76:79], v[172:175], v[202:205], v[76:79]
	v_mfma_f32_16x16x32_bf16 v[68:71], v[164:167], v[210:213], v[68:71]
	v_mfma_f32_16x16x32_bf16 v[64:67], v[172:175], v[210:213], v[64:67]
	s_setprio 0
	s_barrier
	s_add_u32 s98, s26, 0x80
	s_addc_u32 s99, s27, 0
	s_add_i32 s42, s48, s2
	s_mov_b32 m0, s42
	ds_read_b128 v[176:179], v143 offset:16384
	ds_read_b128 v[180:183], v143 offset:17408
	ds_read_b128 v[184:187], v143 offset:18432
	ds_read_b128 v[188:191], v143 offset:19456
	ds_read_b128 v[198:201], v143 offset:20480
	ds_read_b128 v[202:205], v143 offset:21504
	ds_read_b128 v[206:209], v143 offset:22528
	ds_read_b128 v[210:213], v143 offset:23552
	global_load_lds_dwordx4 v196, s[26:27]
	s_add_i32 m0, s42, 0x2000
	s_add_u32 s46, s26, 0x100000
	s_addc_u32 s47, s27, 0
	s_add_i32 s42, s90, s2
	global_load_lds_dwordx4 v128, s[26:27]
	s_mov_b32 m0, s42
	s_nop 0
	global_load_lds_dwordx4 v196, s[46:47]
	s_add_i32 m0, s42, 0x2000
	s_nop 0
	global_load_lds_dwordx4 v128, s[46:47]
	s_waitcnt vmcnt(6)
	s_waitcnt lgkmcnt(0)
	s_barrier
; #define PG8_STAGE(bufoff, gbase, voff) do { _Pragma("unroll") for (int _i = 0; _i < 2; ++_i) \
;         __builtin_amdgcn_global_load_lds((const unsigned*)((const char*)(gbase) + (voff)[_i]), (LAS unsigned*)(lds + (bufoff) + ldsw + _i * 8192), 16, 0, 0); } while (0)
; #define PG8_LDA(dst, b, h) do { _Pragma("unroll") for (int m = 0; m < 4; ++m) _Pragma("unroll") for (int k = 0; k < 2; ++k) dst[m][k] = *(const LAS bf16x8*)(lds + PG8_SA(b, h) + aoff + m * 2048 + k * 1024); } while (0)
; #define PG8_LDB(dst, b, h) do { _Pragma("unroll") for (int n = 0; n < 2; ++n) _Pragma("unroll") for (int k = 0; k < 2; ++k) dst[n][k] = *(const LAS bf16x8*)(lds + PG8_SB(b, h) + boff + n * 2048 + k * 1024); } while (0)
; #define PG8_MMA(ai, bj, At, Bt) do { __builtin_amdgcn_s_setprio(1); _Pragma("unroll") for (int m = 0; m < 4; ++m) _Pragma("unroll") for (int n = 0; n < 2; ++n) _Pragma("unroll") for (int k = 0; k < 2; ++k) \
;         acc[ai][bj][m][n] = __builtin_amdgcn_mfma_f32_16x16x32_bf16(Bt[n][k], At[m][k], acc[ai][bj][m][n], 0, 0, 0); __builtin_amdgcn_s_setprio(0); } while (0)
; #define PG8_WAIT_V(n) asm volatile("s_waitcnt vmcnt(" #n ")" ::: "memory")
; #define PG8_WAIT_L(n) asm volatile("s_waitcnt lgkmcnt(" #n ")" ::: "memory")
; #define PG8_BAR __builtin_amdgcn_s_barrier()
; #define PG8_SCHED __builtin_amdgcn_sched_barrier(0)
; template <class Epi, class Sched, bool ALIGN_EPI = false, bool SP2 = false>
; __device__ __forceinline__ void gemm_phase(LAS unsigned char* lds, const Gemm g, const Sched& S, const Epi& E) {
;     ...
;             PG8_WAIT_V(8); PG8_WAIT_L(0); PG8_BAR; PG8_MMA(1, 0, At, B0); PG8_MMA(1, 1, At, B1); PG8_BAR; PG8_SCHED;
;             PG8_LDB(B0, 1, 0); PG8_LDB(B1, 1, 1); PG8_SCHED; PG8_LDA(At, 1, 0); PG8_STAGE(PG8_SA(0, 1), a2 + hstep, voffA);
	s_setprio 1
	s_waitcnt lgkmcnt(0)
	v_mfma_f32_16x16x32_bf16 v[60:63], v[144:147], v[176:179], v[60:63]
	v_mfma_f32_16x16x32_bf16 v[56:59], v[152:155], v[176:179], v[56:59]
	v_mfma_f32_16x16x32_bf16 v[52:55], v[144:147], v[184:187], v[52:55]
	v_mfma_f32_16x16x32_bf16 v[44:47], v[152:155], v[184:187], v[44:47]
	v_mfma_f32_16x16x32_bf16 v[36:39], v[144:147], v[198:201], v[36:39]
	v_mfma_f32_16x16x32_bf16 v[28:31], v[152:155], v[198:201], v[28:31]
	v_mfma_f32_16x16x32_bf16 v[20:23], v[144:147], v[206:209], v[20:23]
	v_mfma_f32_16x16x32_bf16 v[12:15], v[152:155], v[206:209], v[12:15]
	v_mfma_f32_16x16x32_bf16 v[60:63], v[148:151], v[180:183], v[60:63]
	v_mfma_f32_16x16x32_bf16 v[56:59], v[156:159], v[180:183], v[56:59]
	v_mfma_f32_16x16x32_bf16 v[52:55], v[148:151], v[188:191], v[52:55]
	v_mfma_f32_16x16x32_bf16 v[44:47], v[156:159], v[188:191], v[44:47]
	v_mfma_f32_16x16x32_bf16 v[36:39], v[148:151], v[202:205], v[36:39]
	v_mfma_f32_16x16x32_bf16 v[28:31], v[156:159], v[202:205], v[28:31]
	v_mfma_f32_16x16x32_bf16 v[20:23], v[148:151], v[210:213], v[20:23]
	v_mfma_f32_16x16x32_bf16 v[12:15], v[156:159], v[210:213], v[12:15]
	s_setprio 0
	s_setprio 1
	v_mfma_f32_16x16x32_bf16 v[48:51], v[160:163], v[176:179], v[48:51]
	v_mfma_f32_16x16x32_bf16 v[40:43], v[168:171], v[176:179], v[40:43]
	v_mfma_f32_16x16x32_bf16 v[32:35], v[160:163], v[184:187], v[32:35]
	v_mfma_f32_16x16x32_bf16 v[24:27], v[168:171], v[184:187], v[24:27]
	v_mfma_f32_16x16x32_bf16 v[16:19], v[160:163], v[198:201], v[16:19]
	v_mfma_f32_16x16x32_bf16 v[8:11], v[168:171], v[198:201], v[8:11]
	v_mfma_f32_16x16x32_bf16 v[4:7], v[160:163], v[206:209], v[4:7]
	v_mfma_f32_16x16x32_bf16 v[0:3], v[168:171], v[206:209], v[0:3]
	v_mfma_f32_16x16x32_bf16 v[48:51], v[164:167], v[180:183], v[48:51]
	v_mfma_f32_16x16x32_bf16 v[40:43], v[172:175], v[180:183], v[40:43]
	v_mfma_f32_16x16x32_bf16 v[32:35], v[164:167], v[188:191], v[32:35]
	v_mfma_f32_16x16x32_bf16 v[24:27], v[172:175], v[188:191], v[24:27]
	v_mfma_f32_16x16x32_bf16 v[16:19], v[164:167], v[202:205], v[16:19]
	v_mfma_f32_16x16x32_bf16 v[8:11], v[172:175], v[202:205], v[8:11]
	v_mfma_f32_16x16x32_bf16 v[4:7], v[164:167], v[210:213], v[4:7]
	v_mfma_f32_16x16x32_bf16 v[0:3], v[172:175], v[210:213], v[0:3]
	s_setprio 0
	s_barrier
	v_add_u32_e32 v156, s91, v141
	v_add_u32_e32 v172, s58, v141
	ds_read_b128 v[144:147], v156
	ds_read_b128 v[148:151], v156 offset:1024
	ds_read_b128 v[152:155], v156 offset:2048
	ds_read_b128 v[156:159], v156 offset:3072
	ds_read_b128 v[160:163], v172
	ds_read_b128 v[164:167], v172 offset:1024
	ds_read_b128 v[168:171], v172 offset:2048
	ds_read_b128 v[172:175], v172 offset:3072
	s_mov_b32 m0, s3
	s_nop 0
	global_load_lds_dwordx4 v132, s[28:29]
	s_mov_b32 m0, s6
	s_nop 0
	global_load_lds_dwordx4 v130, s[28:29]
	s_add_u32 s28, s28, 0x100000
	s_addc_u32 s29, s29, 0
	s_mov_b32 m0, s7
	ds_read_b128 v[176:179], v143 offset:32768
	ds_read_b128 v[180:183], v143 offset:33792
	ds_read_b128 v[184:187], v143 offset:34816
	ds_read_b128 v[188:191], v143 offset:35840
	ds_read_b128 v[198:201], v143 offset:36864
	ds_read_b128 v[202:205], v143 offset:37888
	ds_read_b128 v[206:209], v143 offset:38912
	ds_read_b128 v[210:213], v143 offset:39936
	global_load_lds_dwordx4 v132, s[28:29]
	s_mov_b32 m0, s17
	s_nop 0
	global_load_lds_dwordx4 v130, s[28:29]
	s_waitcnt vmcnt(8)
	s_waitcnt lgkmcnt(0)
	s_barrier
; #define PG8_STAGE(bufoff, gbase, voff) do { _Pragma("unroll") for (int _i = 0; _i < 2; ++_i) \
;         __builtin_amdgcn_global_load_lds((const unsigned*)((const char*)(gbase) + (voff)[_i]), (LAS unsigned*)(lds + (bufoff) + ldsw + _i * 8192), 16, 0, 0); } while (0)
; #define PG8_LDA(dst, b, h) do { _Pragma("unroll") for (int m = 0; m < 4; ++m) _Pragma("unroll") for (int k = 0; k < 2; ++k) dst[m][k] = *(const LAS bf16x8*)(lds + PG8_SA(b, h) + aoff + m * 2048 + k * 1024); } while (0)
; #define PG8_MMA(ai, bj, At, Bt) do { __builtin_amdgcn_s_setprio(1); _Pragma("unroll") for (int m = 0; m < 4; ++m) _Pragma("unroll") for (int n = 0; n < 2; ++n) _Pragma("unroll") for (int k = 0; k < 2; ++k) \
;         acc[ai][bj][m][n] = __builtin_amdgcn_mfma_f32_16x16x32_bf16(Bt[n][k], At[m][k], acc[ai][bj][m][n], 0, 0, 0); __builtin_amdgcn_s_setprio(0); } while (0)
; #define PG8_WAIT_V(n) asm volatile("s_waitcnt vmcnt(" #n ")" ::: "memory")
; #define PG8_WAIT_L(n) asm volatile("s_waitcnt lgkmcnt(" #n ")" ::: "memory")
; #define PG8_BAR __builtin_amdgcn_s_barrier()
; #define PG8_SCHED __builtin_amdgcn_sched_barrier(0)
; template <class Epi, class Sched, bool ALIGN_EPI = false, bool SP2 = false>
; __device__ __forceinline__ void gemm_phase(LAS unsigned char* lds, const Gemm g, const Sched& S, const Epi& E) {
;     ...
;             PG8_WAIT_V(8); PG8_WAIT_L(0); PG8_BAR; PG8_MMA(0, 0, At, B0); PG8_MMA(0, 1, At, B1); PG8_BAR; PG8_SCHED;
;             PG8_LDA(At, 1, 1); PG8_STAGE(PG8_SB(1, 0), b3, voffB); PG8_STAGE(PG8_SB(1, 1), b3 + hstep, voffB); PG8_STAGE(PG8_SA(1, 0), a3, voffA);
;             PG8_WAIT_V(8); PG8_WAIT_L(0); PG8_BAR; PG8_MMA(1, 0, At, B0); PG8_MMA(1, 1, At, B1); PG8_BAR; PG8_SCHED;
	s_setprio 1
	s_waitcnt lgkmcnt(0)
	v_mfma_f32_16x16x32_bf16 v[124:127], v[144:147], v[176:179], v[124:127]
	v_mfma_f32_16x16x32_bf16 v[120:123], v[152:155], v[176:179], v[120:123]
	v_mfma_f32_16x16x32_bf16 v[116:119], v[144:147], v[184:187], v[116:119]
	v_mfma_f32_16x16x32_bf16 v[108:111], v[152:155], v[184:187], v[108:111]
	v_mfma_f32_16x16x32_bf16 v[100:103], v[144:147], v[198:201], v[100:103]
	v_mfma_f32_16x16x32_bf16 v[92:95], v[152:155], v[198:201], v[92:95]
	v_mfma_f32_16x16x32_bf16 v[80:83], v[144:147], v[206:209], v[80:83]
	v_mfma_f32_16x16x32_bf16 v[72:75], v[152:155], v[206:209], v[72:75]
	v_mfma_f32_16x16x32_bf16 v[124:127], v[148:151], v[180:183], v[124:127]
	v_mfma_f32_16x16x32_bf16 v[120:123], v[156:159], v[180:183], v[120:123]
	v_mfma_f32_16x16x32_bf16 v[116:119], v[148:151], v[188:191], v[116:119]
	v_mfma_f32_16x16x32_bf16 v[108:111], v[156:159], v[188:191], v[108:111]
	v_mfma_f32_16x16x32_bf16 v[100:103], v[148:151], v[202:205], v[100:103]
	v_mfma_f32_16x16x32_bf16 v[92:95], v[156:159], v[202:205], v[92:95]
	v_mfma_f32_16x16x32_bf16 v[80:83], v[148:151], v[210:213], v[80:83]
	v_mfma_f32_16x16x32_bf16 v[72:75], v[156:159], v[210:213], v[72:75]
	s_setprio 0
	s_setprio 1
	v_mfma_f32_16x16x32_bf16 v[112:115], v[160:163], v[176:179], v[112:115]
	v_mfma_f32_16x16x32_bf16 v[104:107], v[168:171], v[176:179], v[104:107]
	v_mfma_f32_16x16x32_bf16 v[96:99], v[160:163], v[184:187], v[96:99]
	v_mfma_f32_16x16x32_bf16 v[88:91], v[168:171], v[184:187], v[88:91]
	v_mfma_f32_16x16x32_bf16 v[84:87], v[160:163], v[198:201], v[84:87]
	v_mfma_f32_16x16x32_bf16 v[76:79], v[168:171], v[198:201], v[76:79]
	v_mfma_f32_16x16x32_bf16 v[68:71], v[160:163], v[206:209], v[68:71]
	v_mfma_f32_16x16x32_bf16 v[64:67], v[168:171], v[206:209], v[64:67]
	v_mfma_f32_16x16x32_bf16 v[112:115], v[164:167], v[180:183], v[112:115]
	v_mfma_f32_16x16x32_bf16 v[104:107], v[172:175], v[180:183], v[104:107]
	v_mfma_f32_16x16x32_bf16 v[96:99], v[164:167], v[188:191], v[96:99]
	v_mfma_f32_16x16x32_bf16 v[88:91], v[172:175], v[188:191], v[88:91]
	v_mfma_f32_16x16x32_bf16 v[84:87], v[164:167], v[202:205], v[84:87]
	v_mfma_f32_16x16x32_bf16 v[76:79], v[172:175], v[202:205], v[76:79]
	v_mfma_f32_16x16x32_bf16 v[68:71], v[164:167], v[210:213], v[68:71]
	v_mfma_f32_16x16x32_bf16 v[64:67], v[172:175], v[210:213], v[64:67]
	s_setprio 0
	s_barrier
	s_add_i32 s28, s91, s2
	s_mov_b32 m0, s28
	ds_read_b128 v[176:179], v143 offset:49152
	ds_read_b128 v[180:183], v143 offset:50176
	ds_read_b128 v[184:187], v143 offset:51200
	ds_read_b128 v[188:191], v143 offset:52224
	ds_read_b128 v[198:201], v143 offset:53248
	ds_read_b128 v[202:205], v143 offset:54272
	ds_read_b128 v[206:209], v143 offset:55296
	ds_read_b128 v[210:213], v143 offset:56320
	global_load_lds_dwordx4 v196, s[98:99]
	s_add_i32 m0, s28, 0x2000
	s_add_u32 s26, s26, 0x100080
	s_addc_u32 s27, s27, 0
	s_add_i32 s28, s58, s2
	global_load_lds_dwordx4 v128, s[98:99]
	s_mov_b32 m0, s28
	s_nop 0
	global_load_lds_dwordx4 v196, s[26:27]
	s_add_i32 m0, s28, 0x2000
	s_nop 0
	global_load_lds_dwordx4 v128, s[26:27]
	s_waitcnt vmcnt(6)
	s_waitcnt lgkmcnt(0)
	s_barrier
	s_setprio 1
	s_waitcnt lgkmcnt(0)
	v_mfma_f32_16x16x32_bf16 v[60:63], v[144:147], v[176:179], v[60:63]
	v_mfma_f32_16x16x32_bf16 v[56:59], v[152:155], v[176:179], v[56:59]
	v_mfma_f32_16x16x32_bf16 v[52:55], v[144:147], v[184:187], v[52:55]
	v_mfma_f32_16x16x32_bf16 v[44:47], v[152:155], v[184:187], v[44:47]
	v_mfma_f32_16x16x32_bf16 v[36:39], v[144:147], v[198:201], v[36:39]
	v_mfma_f32_16x16x32_bf16 v[28:31], v[152:155], v[198:201], v[28:31]
	v_mfma_f32_16x16x32_bf16 v[20:23], v[144:147], v[206:209], v[20:23]
	v_mfma_f32_16x16x32_bf16 v[12:15], v[152:155], v[206:209], v[12:15]
	v_mfma_f32_16x16x32_bf16 v[60:63], v[148:151], v[180:183], v[60:63]
	v_mfma_f32_16x16x32_bf16 v[56:59], v[156:159], v[180:183], v[56:59]
	v_mfma_f32_16x16x32_bf16 v[52:55], v[148:151], v[188:191], v[52:55]
	v_mfma_f32_16x16x32_bf16 v[44:47], v[156:159], v[188:191], v[44:47]
	v_mfma_f32_16x16x32_bf16 v[36:39], v[148:151], v[202:205], v[36:39]
	v_mfma_f32_16x16x32_bf16 v[28:31], v[156:159], v[202:205], v[28:31]
	v_mfma_f32_16x16x32_bf16 v[20:23], v[148:151], v[210:213], v[20:23]
	v_mfma_f32_16x16x32_bf16 v[12:15], v[156:159], v[210:213], v[12:15]
	s_setprio 0
	s_setprio 1
	v_mfma_f32_16x16x32_bf16 v[48:51], v[160:163], v[176:179], v[48:51]
	v_mfma_f32_16x16x32_bf16 v[40:43], v[168:171], v[176:179], v[40:43]
	v_mfma_f32_16x16x32_bf16 v[32:35], v[160:163], v[184:187], v[32:35]
	v_mfma_f32_16x16x32_bf16 v[24:27], v[168:171], v[184:187], v[24:27]
	v_mfma_f32_16x16x32_bf16 v[16:19], v[160:163], v[198:201], v[16:19]
	v_mfma_f32_16x16x32_bf16 v[8:11], v[168:171], v[198:201], v[8:11]
	v_mfma_f32_16x16x32_bf16 v[4:7], v[160:163], v[206:209], v[4:7]
	v_mfma_f32_16x16x32_bf16 v[0:3], v[168:171], v[206:209], v[0:3]
	v_mfma_f32_16x16x32_bf16 v[48:51], v[164:167], v[180:183], v[48:51]
	v_mfma_f32_16x16x32_bf16 v[40:43], v[172:175], v[180:183], v[40:43]
	v_mfma_f32_16x16x32_bf16 v[32:35], v[164:167], v[188:191], v[32:35]
	v_mfma_f32_16x16x32_bf16 v[24:27], v[172:175], v[188:191], v[24:27]
	v_mfma_f32_16x16x32_bf16 v[16:19], v[164:167], v[202:205], v[16:19]
	v_mfma_f32_16x16x32_bf16 v[8:11], v[172:175], v[202:205], v[8:11]
	v_mfma_f32_16x16x32_bf16 v[4:7], v[164:167], v[210:213], v[4:7]
	v_mfma_f32_16x16x32_bf16 v[0:3], v[172:175], v[210:213], v[0:3]
	s_setprio 0
	s_barrier
	s_add_i32 s41, s41, 2
	s_add_u32 s24, s24, 0x100
	s_addc_u32 s25, s25, 0
	s_add_u32 s39, s39, 0x100
	s_addc_u32 s40, s40, 0
	s_cmp_gt_u32 s41, 61
	s_cbranch_scc0 .LBB0_510
	s_and_b64 vcc, exec, s[10:11]
	s_cbranch_vccz .LBB0_513
	s_barrier

; #define PG8_STAGE(bufoff, gbase, voff) do { _Pragma("unroll") for (int _i = 0; _i < 2; ++_i) \
;         __builtin_amdgcn_global_load_lds((const unsigned*)((const char*)(gbase) + (voff)[_i]), (LAS unsigned*)(lds + (bufoff) + ldsw + _i * 8192), 16, 0, 0); } while (0)
; #define PG8_LDA(dst, b, h) do { _Pragma("unroll") for (int m = 0; m < 4; ++m) _Pragma("unroll") for (int k = 0; k < 2; ++k) dst[m][k] = *(const LAS bf16x8*)(lds + PG8_SA(b, h) + aoff + m * 2048 + k * 1024); } while (0)
; #define PG8_LDB(dst, b, h) do { _Pragma("unroll") for (int n = 0; n < 2; ++n) _Pragma("unroll") for (int k = 0; k < 2; ++k) dst[n][k] = *(const LAS bf16x8*)(lds + PG8_SB(b, h) + boff + n * 2048 + k * 1024); } while (0)
; #define PG8_MMA(ai, bj, At, Bt) do { __builtin_amdgcn_s_setprio(1); _Pragma("unroll") for (int m = 0; m < 4; ++m) _Pragma("unroll") for (int n = 0; n < 2; ++n) _Pragma("unroll") for (int k = 0; k < 2; ++k) \
;         acc[ai][bj][m][n] = __builtin_amdgcn_mfma_f32_16x16x32_bf16(Bt[n][k], At[m][k], acc[ai][bj][m][n], 0, 0, 0); __builtin_amdgcn_s_setprio(0); } while (0)
; #define PG8_WAIT_V(n) asm volatile("s_waitcnt vmcnt(" #n ")" ::: "memory")
; #define PG8_WAIT_L(n) asm volatile("s_waitcnt lgkmcnt(" #n ")" ::: "memory")
; #define PG8_BAR __builtin_amdgcn_s_barrier()
; #define PG8_SCHED __builtin_amdgcn_sched_barrier(0)
; template <class Epi, class Sched, bool ALIGN_EPI = false, bool SP2 = false>
; __device__ __forceinline__ void gemm_phase(LAS unsigned char* lds, const Gemm g, const Sched& S, const Epi& E) {
;     ...
;             PG8_LDB(B0, 0, 0); PG8_LDB(B1, 0, 1); PG8_SCHED; PG8_LDA(At, 0, 0); PG8_STAGE(PG8_SA(1, 1), a1 + hstep, voffA);
;             PG8_WAIT_V(8); PG8_WAIT_L(0); PG8_BAR; PG8_MMA(0, 0, At, B0); PG8_MMA(0, 1, At, B1); PG8_BAR; PG8_SCHED;
;             PG8_LDA(At, 0, 1); PG8_STAGE(PG8_SB(0, 0), b2, voffB); PG8_STAGE(PG8_SB(0, 1), b2 + hstep, voffB); PG8_STAGE(PG8_SA(0, 0), a2, voffA);
.LBB0_832:
	v_add_u32_e32 v150, s48, v157
	v_add_u32_e32 v154, s90, v157
	ds_read_b128 v[128:131], v150
	ds_read_b128 v[132:135], v150 offset:1024
	ds_read_b128 v[146:149], v150 offset:2048
	ds_read_b128 v[150:153], v150 offset:3072
	ds_read_b128 v[160:163], v154
	ds_read_b128 v[164:167], v154 offset:1024
	ds_read_b128 v[168:171], v154 offset:2048
	ds_read_b128 v[172:175], v154 offset:3072
	s_add_u32 s100, s10, 0xfff00000
	s_addc_u32 s101, s11, -1
	s_add_u32 s34, s10, 0xfff00080
	s_addc_u32 s35, s11, -1
	s_cmp_eq_u32 s62, 60
	s_cselect_b32 s37, s27, s35
	s_cselect_b32 s36, s47, s34
	s_cselect_b32 s35, s25, s59
	s_cselect_b32 s34, s49, s54
	s_add_i32 m0, s3, 0xc000
	ds_read_b128 v[176:179], v159
	ds_read_b128 v[180:183], v159 offset:1024
	ds_read_b128 v[184:187], v159 offset:2048
	ds_read_b128 v[188:191], v159 offset:3072
	ds_read_b128 v[198:201], v159 offset:4096
	ds_read_b128 v[202:205], v159 offset:5120
	ds_read_b128 v[206:209], v159 offset:6144
	ds_read_b128 v[210:213], v159 offset:7168
	s_mov_b32 m0, s41
	s_nop 0
	global_load_lds_dwordx4 v140, s[100:101]
	s_mov_b32 m0, s42
	s_nop 0
	global_load_lds_dwordx4 v138, s[100:101]
	s_add_i32 m0, s3, 0xc000
	s_nop 0
	global_load_lds_dwordx4 v142, s[10:11]
	s_add_i32 m0, s3, 0xe000
	s_nop 0
	global_load_lds_dwordx4 v144, s[10:11]
	s_waitcnt vmcnt(8)
	s_waitcnt lgkmcnt(0)
	s_barrier
	s_setprio 1
	s_waitcnt lgkmcnt(0)
	v_mfma_f32_16x16x32_bf16 v[124:127], v[128:131], v[176:179], v[124:127]
	v_mfma_f32_16x16x32_bf16 v[120:123], v[146:149], v[176:179], v[120:123]
	v_mfma_f32_16x16x32_bf16 v[108:111], v[128:131], v[184:187], v[108:111]
	v_mfma_f32_16x16x32_bf16 v[104:107], v[146:149], v[184:187], v[104:107]
	v_mfma_f32_16x16x32_bf16 v[92:95], v[128:131], v[198:201], v[92:95]
	v_mfma_f32_16x16x32_bf16 v[88:91], v[146:149], v[198:201], v[88:91]
	v_mfma_f32_16x16x32_bf16 v[76:79], v[128:131], v[206:209], v[76:79]
	v_mfma_f32_16x16x32_bf16 v[72:75], v[146:149], v[206:209], v[72:75]
	v_mfma_f32_16x16x32_bf16 v[124:127], v[132:135], v[180:183], v[124:127]
	v_mfma_f32_16x16x32_bf16 v[120:123], v[150:153], v[180:183], v[120:123]
	v_mfma_f32_16x16x32_bf16 v[108:111], v[132:135], v[188:191], v[108:111]
	v_mfma_f32_16x16x32_bf16 v[104:107], v[150:153], v[188:191], v[104:107]
	v_mfma_f32_16x16x32_bf16 v[92:95], v[132:135], v[202:205], v[92:95]
	v_mfma_f32_16x16x32_bf16 v[88:91], v[150:153], v[202:205], v[88:91]
	v_mfma_f32_16x16x32_bf16 v[76:79], v[132:135], v[210:213], v[76:79]
	v_mfma_f32_16x16x32_bf16 v[72:75], v[150:153], v[210:213], v[72:75]
	s_setprio 0
	s_setprio 1
	v_mfma_f32_16x16x32_bf16 v[116:119], v[160:163], v[176:179], v[116:119]
	v_mfma_f32_16x16x32_bf16 v[112:115], v[168:171], v[176:179], v[112:115]
	v_mfma_f32_16x16x32_bf16 v[100:103], v[160:163], v[184:187], v[100:103]
	v_mfma_f32_16x16x32_bf16 v[96:99], v[168:171], v[184:187], v[96:99]
	v_mfma_f32_16x16x32_bf16 v[84:87], v[160:163], v[198:201], v[84:87]
	v_mfma_f32_16x16x32_bf16 v[80:83], v[168:171], v[198:201], v[80:83]
	v_mfma_f32_16x16x32_bf16 v[68:71], v[160:163], v[206:209], v[68:71]
	v_mfma_f32_16x16x32_bf16 v[64:67], v[168:171], v[206:209], v[64:67]
	v_mfma_f32_16x16x32_bf16 v[116:119], v[164:167], v[180:183], v[116:119]
	v_mfma_f32_16x16x32_bf16 v[112:115], v[172:175], v[180:183], v[112:115]
	v_mfma_f32_16x16x32_bf16 v[100:103], v[164:167], v[188:191], v[100:103]
	v_mfma_f32_16x16x32_bf16 v[96:99], v[172:175], v[188:191], v[96:99]
	v_mfma_f32_16x16x32_bf16 v[84:87], v[164:167], v[202:205], v[84:87]
	v_mfma_f32_16x16x32_bf16 v[80:83], v[172:175], v[202:205], v[80:83]
	v_mfma_f32_16x16x32_bf16 v[68:71], v[164:167], v[210:213], v[68:71]
	v_mfma_f32_16x16x32_bf16 v[64:67], v[172:175], v[210:213], v[64:67]
	s_setprio 0
	s_barrier
	s_add_u32 s98, s34, 0x80
	s_addc_u32 s99, s35, 0
	s_add_i32 s63, s48, s0
	s_mov_b32 m0, s63
	ds_read_b128 v[176:179], v159 offset:16384
	ds_read_b128 v[180:183], v159 offset:17408
	ds_read_b128 v[184:187], v159 offset:18432
	ds_read_b128 v[188:191], v159 offset:19456
	ds_read_b128 v[198:201], v159 offset:20480
	ds_read_b128 v[202:205], v159 offset:21504
	ds_read_b128 v[206:209], v159 offset:22528
	ds_read_b128 v[210:213], v159 offset:23552
	global_load_lds_dwordx4 v196, s[34:35]
	s_add_i32 m0, s63, 0x2000
	s_add_u32 s64, s34, 0x100000
	s_addc_u32 s65, s35, 0
	s_add_i32 s63, s90, s0
	global_load_lds_dwordx4 v136, s[34:35]
	s_mov_b32 m0, s63
	s_nop 0
	global_load_lds_dwordx4 v196, s[64:65]
	s_add_i32 m0, s63, 0x2000
	s_nop 0
	global_load_lds_dwordx4 v136, s[64:65]
	s_waitcnt vmcnt(6)
	s_waitcnt lgkmcnt(0)
	s_barrier
; #define PG8_STAGE(bufoff, gbase, voff) do { _Pragma("unroll") for (int _i = 0; _i < 2; ++_i) \
;         __builtin_amdgcn_global_load_lds((const unsigned*)((const char*)(gbase) + (voff)[_i]), (LAS unsigned*)(lds + (bufoff) + ldsw + _i * 8192), 16, 0, 0); } while (0)
; #define PG8_LDA(dst, b, h) do { _Pragma("unroll") for (int m = 0; m < 4; ++m) _Pragma("unroll") for (int k = 0; k < 2; ++k) dst[m][k] = *(const LAS bf16x8*)(lds + PG8_SA(b, h) + aoff + m * 2048 + k * 1024); } while (0)
; #define PG8_LDB(dst, b, h) do { _Pragma("unroll") for (int n = 0; n < 2; ++n) _Pragma("unroll") for (int k = 0; k < 2; ++k) dst[n][k] = *(const LAS bf16x8*)(lds + PG8_SB(b, h) + boff + n * 2048 + k * 1024); } while (0)
; #define PG8_MMA(ai, bj, At, Bt) do { __builtin_amdgcn_s_setprio(1); _Pragma("unroll") for (int m = 0; m < 4; ++m) _Pragma("unroll") for (int n = 0; n < 2; ++n) _Pragma("unroll") for (int k = 0; k < 2; ++k) \
;         acc[ai][bj][m][n] = __builtin_amdgcn_mfma_f32_16x16x32_bf16(Bt[n][k], At[m][k], acc[ai][bj][m][n], 0, 0, 0); __builtin_amdgcn_s_setprio(0); } while (0)
; #define PG8_WAIT_V(n) asm volatile("s_waitcnt vmcnt(" #n ")" ::: "memory")
; #define PG8_WAIT_L(n) asm volatile("s_waitcnt lgkmcnt(" #n ")" ::: "memory")
; #define PG8_BAR __builtin_amdgcn_s_barrier()
; #define PG8_SCHED __builtin_amdgcn_sched_barrier(0)
; template <class Epi, class Sched, bool ALIGN_EPI = false, bool SP2 = false>
; __device__ __forceinline__ void gemm_phase(LAS unsigned char* lds, const Gemm g, const Sched& S, const Epi& E) {
;     ...
;             PG8_WAIT_V(8); PG8_WAIT_L(0); PG8_BAR; PG8_MMA(1, 0, At, B0); PG8_MMA(1, 1, At, B1); PG8_BAR; PG8_SCHED;
;             PG8_LDB(B0, 1, 0); PG8_LDB(B1, 1, 1); PG8_SCHED; PG8_LDA(At, 1, 0); PG8_STAGE(PG8_SA(0, 1), a2 + hstep, voffA);
	s_setprio 1
	s_waitcnt lgkmcnt(0)
	v_mfma_f32_16x16x32_bf16 v[60:63], v[128:131], v[176:179], v[60:63]
	v_mfma_f32_16x16x32_bf16 v[56:59], v[146:149], v[176:179], v[56:59]
	v_mfma_f32_16x16x32_bf16 v[44:47], v[128:131], v[184:187], v[44:47]
	v_mfma_f32_16x16x32_bf16 v[40:43], v[146:149], v[184:187], v[40:43]
	v_mfma_f32_16x16x32_bf16 v[28:31], v[128:131], v[198:201], v[28:31]
	v_mfma_f32_16x16x32_bf16 v[24:27], v[146:149], v[198:201], v[24:27]
	v_mfma_f32_16x16x32_bf16 v[12:15], v[128:131], v[206:209], v[12:15]
	v_mfma_f32_16x16x32_bf16 v[8:11], v[146:149], v[206:209], v[8:11]
	v_mfma_f32_16x16x32_bf16 v[60:63], v[132:135], v[180:183], v[60:63]
	v_mfma_f32_16x16x32_bf16 v[56:59], v[150:153], v[180:183], v[56:59]
	v_mfma_f32_16x16x32_bf16 v[44:47], v[132:135], v[188:191], v[44:47]
	v_mfma_f32_16x16x32_bf16 v[40:43], v[150:153], v[188:191], v[40:43]
	v_mfma_f32_16x16x32_bf16 v[28:31], v[132:135], v[202:205], v[28:31]
	v_mfma_f32_16x16x32_bf16 v[24:27], v[150:153], v[202:205], v[24:27]
	v_mfma_f32_16x16x32_bf16 v[12:15], v[132:135], v[210:213], v[12:15]
	v_mfma_f32_16x16x32_bf16 v[8:11], v[150:153], v[210:213], v[8:11]
	s_setprio 0
	s_setprio 1
	v_mfma_f32_16x16x32_bf16 v[52:55], v[160:163], v[176:179], v[52:55]
	v_mfma_f32_16x16x32_bf16 v[48:51], v[168:171], v[176:179], v[48:51]
	v_mfma_f32_16x16x32_bf16 v[36:39], v[160:163], v[184:187], v[36:39]
	v_mfma_f32_16x16x32_bf16 v[32:35], v[168:171], v[184:187], v[32:35]
	v_mfma_f32_16x16x32_bf16 v[20:23], v[160:163], v[198:201], v[20:23]
	v_mfma_f32_16x16x32_bf16 v[16:19], v[168:171], v[198:201], v[16:19]
	v_mfma_f32_16x16x32_bf16 v[4:7], v[160:163], v[206:209], v[4:7]
	v_mfma_f32_16x16x32_bf16 v[0:3], v[168:171], v[206:209], v[0:3]
	v_mfma_f32_16x16x32_bf16 v[52:55], v[164:167], v[180:183], v[52:55]
	v_mfma_f32_16x16x32_bf16 v[48:51], v[172:175], v[180:183], v[48:51]
	v_mfma_f32_16x16x32_bf16 v[36:39], v[164:167], v[188:191], v[36:39]
	v_mfma_f32_16x16x32_bf16 v[32:35], v[172:175], v[188:191], v[32:35]
	v_mfma_f32_16x16x32_bf16 v[20:23], v[164:167], v[202:205], v[20:23]
	v_mfma_f32_16x16x32_bf16 v[16:19], v[172:175], v[202:205], v[16:19]
	v_mfma_f32_16x16x32_bf16 v[4:7], v[164:167], v[210:213], v[4:7]
	v_mfma_f32_16x16x32_bf16 v[0:3], v[172:175], v[210:213], v[0:3]
	s_setprio 0
	s_barrier
	v_add_u32_e32 v150, s91, v157
	v_add_u32_e32 v172, s58, v157
	ds_read_b128 v[128:131], v150
	ds_read_b128 v[132:135], v150 offset:1024
	ds_read_b128 v[146:149], v150 offset:2048
	ds_read_b128 v[150:153], v150 offset:3072
	ds_read_b128 v[160:163], v172
	ds_read_b128 v[164:167], v172 offset:1024
	ds_read_b128 v[168:171], v172 offset:2048
	ds_read_b128 v[172:175], v172 offset:3072
	s_mov_b32 m0, s3
	s_nop 0
	global_load_lds_dwordx4 v140, s[36:37]
	s_mov_b32 m0, s17
	s_nop 0
	global_load_lds_dwordx4 v138, s[36:37]
	s_add_u32 s36, s36, 0x100000
	s_addc_u32 s37, s37, 0
	s_mov_b32 m0, s38
	ds_read_b128 v[176:179], v159 offset:32768
	ds_read_b128 v[180:183], v159 offset:33792
	ds_read_b128 v[184:187], v159 offset:34816
	ds_read_b128 v[188:191], v159 offset:35840
	ds_read_b128 v[198:201], v159 offset:36864
	ds_read_b128 v[202:205], v159 offset:37888
	ds_read_b128 v[206:209], v159 offset:38912
	ds_read_b128 v[210:213], v159 offset:39936
	global_load_lds_dwordx4 v140, s[36:37]
	s_mov_b32 m0, s39
	s_nop 0
	global_load_lds_dwordx4 v138, s[36:37]
	s_waitcnt vmcnt(8)
	s_waitcnt lgkmcnt(0)
	s_barrier
; #define PG8_STAGE(bufoff, gbase, voff) do { _Pragma("unroll") for (int _i = 0; _i < 2; ++_i) \
;         __builtin_amdgcn_global_load_lds((const unsigned*)((const char*)(gbase) + (voff)[_i]), (LAS unsigned*)(lds + (bufoff) + ldsw + _i * 8192), 16, 0, 0); } while (0)
; #define PG8_LDA(dst, b, h) do { _Pragma("unroll") for (int m = 0; m < 4; ++m) _Pragma("unroll") for (int k = 0; k < 2; ++k) dst[m][k] = *(const LAS bf16x8*)(lds + PG8_SA(b, h) + aoff + m * 2048 + k * 1024); } while (0)
; #define PG8_MMA(ai, bj, At, Bt) do { __builtin_amdgcn_s_setprio(1); _Pragma("unroll") for (int m = 0; m < 4; ++m) _Pragma("unroll") for (int n = 0; n < 2; ++n) _Pragma("unroll") for (int k = 0; k < 2; ++k) \
;         acc[ai][bj][m][n] = __builtin_amdgcn_mfma_f32_16x16x32_bf16(Bt[n][k], At[m][k], acc[ai][bj][m][n], 0, 0, 0); __builtin_amdgcn_s_setprio(0); } while (0)
; #define PG8_WAIT_V(n) asm volatile("s_waitcnt vmcnt(" #n ")" ::: "memory")
; #define PG8_WAIT_L(n) asm volatile("s_waitcnt lgkmcnt(" #n ")" ::: "memory")
; #define PG8_BAR __builtin_amdgcn_s_barrier()
; #define PG8_SCHED __builtin_amdgcn_sched_barrier(0)
; template <class Epi, class Sched, bool ALIGN_EPI = false, bool SP2 = false>
; __device__ __forceinline__ void gemm_phase(LAS unsigned char* lds, const Gemm g, const Sched& S, const Epi& E) {
;     ...
;             PG8_WAIT_V(8); PG8_WAIT_L(0); PG8_BAR; PG8_MMA(0, 0, At, B0); PG8_MMA(0, 1, At, B1); PG8_BAR; PG8_SCHED;
;             PG8_LDA(At, 1, 1); PG8_STAGE(PG8_SB(1, 0), b3, voffB); PG8_STAGE(PG8_SB(1, 1), b3 + hstep, voffB); PG8_STAGE(PG8_SA(1, 0), a3, voffA);
;             PG8_WAIT_V(8); PG8_WAIT_L(0); PG8_BAR; PG8_MMA(1, 0, At, B0); PG8_MMA(1, 1, At, B1); PG8_BAR; PG8_SCHED;
	s_setprio 1
	s_waitcnt lgkmcnt(0)
	v_mfma_f32_16x16x32_bf16 v[124:127], v[128:131], v[176:179], v[124:127]
	v_mfma_f32_16x16x32_bf16 v[120:123], v[146:149], v[176:179], v[120:123]
	v_mfma_f32_16x16x32_bf16 v[108:111], v[128:131], v[184:187], v[108:111]
	v_mfma_f32_16x16x32_bf16 v[104:107], v[146:149], v[184:187], v[104:107]
	v_mfma_f32_16x16x32_bf16 v[92:95], v[128:131], v[198:201], v[92:95]
	v_mfma_f32_16x16x32_bf16 v[88:91], v[146:149], v[198:201], v[88:91]
	v_mfma_f32_16x16x32_bf16 v[76:79], v[128:131], v[206:209], v[76:79]
	v_mfma_f32_16x16x32_bf16 v[72:75], v[146:149], v[206:209], v[72:75]
	v_mfma_f32_16x16x32_bf16 v[124:127], v[132:135], v[180:183], v[124:127]
	v_mfma_f32_16x16x32_bf16 v[120:123], v[150:153], v[180:183], v[120:123]
	v_mfma_f32_16x16x32_bf16 v[108:111], v[132:135], v[188:191], v[108:111]
	v_mfma_f32_16x16x32_bf16 v[104:107], v[150:153], v[188:191], v[104:107]
	v_mfma_f32_16x16x32_bf16 v[92:95], v[132:135], v[202:205], v[92:95]
	v_mfma_f32_16x16x32_bf16 v[88:91], v[150:153], v[202:205], v[88:91]
	v_mfma_f32_16x16x32_bf16 v[76:79], v[132:135], v[210:213], v[76:79]
	v_mfma_f32_16x16x32_bf16 v[72:75], v[150:153], v[210:213], v[72:75]
	s_setprio 0
	s_setprio 1
	v_mfma_f32_16x16x32_bf16 v[116:119], v[160:163], v[176:179], v[116:119]
	v_mfma_f32_16x16x32_bf16 v[112:115], v[168:171], v[176:179], v[112:115]
	v_mfma_f32_16x16x32_bf16 v[100:103], v[160:163], v[184:187], v[100:103]
	v_mfma_f32_16x16x32_bf16 v[96:99], v[168:171], v[184:187], v[96:99]
	v_mfma_f32_16x16x32_bf16 v[84:87], v[160:163], v[198:201], v[84:87]
	v_mfma_f32_16x16x32_bf16 v[80:83], v[168:171], v[198:201], v[80:83]
	v_mfma_f32_16x16x32_bf16 v[68:71], v[160:163], v[206:209], v[68:71]
	v_mfma_f32_16x16x32_bf16 v[64:67], v[168:171], v[206:209], v[64:67]
	v_mfma_f32_16x16x32_bf16 v[116:119], v[164:167], v[180:183], v[116:119]
	v_mfma_f32_16x16x32_bf16 v[112:115], v[172:175], v[180:183], v[112:115]
	v_mfma_f32_16x16x32_bf16 v[100:103], v[164:167], v[188:191], v[100:103]
	v_mfma_f32_16x16x32_bf16 v[96:99], v[172:175], v[188:191], v[96:99]
	v_mfma_f32_16x16x32_bf16 v[84:87], v[164:167], v[202:205], v[84:87]
	v_mfma_f32_16x16x32_bf16 v[80:83], v[172:175], v[202:205], v[80:83]
	v_mfma_f32_16x16x32_bf16 v[68:71], v[164:167], v[210:213], v[68:71]
	v_mfma_f32_16x16x32_bf16 v[64:67], v[172:175], v[210:213], v[64:67]
	s_setprio 0
	s_barrier
	s_add_i32 s36, s91, s0
	s_mov_b32 m0, s36
	ds_read_b128 v[176:179], v159 offset:49152
	ds_read_b128 v[180:183], v159 offset:50176
	ds_read_b128 v[184:187], v159 offset:51200
	ds_read_b128 v[188:191], v159 offset:52224
	ds_read_b128 v[198:201], v159 offset:53248
	ds_read_b128 v[202:205], v159 offset:54272
	ds_read_b128 v[206:209], v159 offset:55296
	ds_read_b128 v[210:213], v159 offset:56320
	global_load_lds_dwordx4 v196, s[98:99]
	s_add_i32 m0, s36, 0x2000
	s_add_u32 s34, s34, 0x100080
	s_addc_u32 s35, s35, 0
	s_add_i32 s36, s58, s0
	global_load_lds_dwordx4 v136, s[98:99]
	s_mov_b32 m0, s36
	s_nop 0
	global_load_lds_dwordx4 v196, s[34:35]
	s_add_i32 m0, s36, 0x2000
	s_nop 0
	global_load_lds_dwordx4 v136, s[34:35]
	s_waitcnt vmcnt(6)
	s_waitcnt lgkmcnt(0)
	s_barrier
	s_setprio 1
	s_waitcnt lgkmcnt(0)
	v_mfma_f32_16x16x32_bf16 v[60:63], v[128:131], v[176:179], v[60:63]
	v_mfma_f32_16x16x32_bf16 v[56:59], v[146:149], v[176:179], v[56:59]
	v_mfma_f32_16x16x32_bf16 v[44:47], v[128:131], v[184:187], v[44:47]
	v_mfma_f32_16x16x32_bf16 v[40:43], v[146:149], v[184:187], v[40:43]
	v_mfma_f32_16x16x32_bf16 v[28:31], v[128:131], v[198:201], v[28:31]
	v_mfma_f32_16x16x32_bf16 v[24:27], v[146:149], v[198:201], v[24:27]
	v_mfma_f32_16x16x32_bf16 v[12:15], v[128:131], v[206:209], v[12:15]
	v_mfma_f32_16x16x32_bf16 v[8:11], v[146:149], v[206:209], v[8:11]
	v_mfma_f32_16x16x32_bf16 v[60:63], v[132:135], v[180:183], v[60:63]
	v_mfma_f32_16x16x32_bf16 v[56:59], v[150:153], v[180:183], v[56:59]
	v_mfma_f32_16x16x32_bf16 v[44:47], v[132:135], v[188:191], v[44:47]
	v_mfma_f32_16x16x32_bf16 v[40:43], v[150:153], v[188:191], v[40:43]
	v_mfma_f32_16x16x32_bf16 v[28:31], v[132:135], v[202:205], v[28:31]
	v_mfma_f32_16x16x32_bf16 v[24:27], v[150:153], v[202:205], v[24:27]
	v_mfma_f32_16x16x32_bf16 v[12:15], v[132:135], v[210:213], v[12:15]
	v_mfma_f32_16x16x32_bf16 v[8:11], v[150:153], v[210:213], v[8:11]
	s_setprio 0
	s_setprio 1
	v_mfma_f32_16x16x32_bf16 v[52:55], v[160:163], v[176:179], v[52:55]
	v_mfma_f32_16x16x32_bf16 v[48:51], v[168:171], v[176:179], v[48:51]
	v_mfma_f32_16x16x32_bf16 v[36:39], v[160:163], v[184:187], v[36:39]
	v_mfma_f32_16x16x32_bf16 v[32:35], v[168:171], v[184:187], v[32:35]
	v_mfma_f32_16x16x32_bf16 v[20:23], v[160:163], v[198:201], v[20:23]
	v_mfma_f32_16x16x32_bf16 v[16:19], v[168:171], v[198:201], v[16:19]
	v_mfma_f32_16x16x32_bf16 v[4:7], v[160:163], v[206:209], v[4:7]
	v_mfma_f32_16x16x32_bf16 v[0:3], v[168:171], v[206:209], v[0:3]
	v_mfma_f32_16x16x32_bf16 v[52:55], v[164:167], v[180:183], v[52:55]
	v_mfma_f32_16x16x32_bf16 v[48:51], v[172:175], v[180:183], v[48:51]
	v_mfma_f32_16x16x32_bf16 v[36:39], v[164:167], v[188:191], v[36:39]
	v_mfma_f32_16x16x32_bf16 v[32:35], v[172:175], v[188:191], v[32:35]
	v_mfma_f32_16x16x32_bf16 v[20:23], v[164:167], v[202:205], v[20:23]
	v_mfma_f32_16x16x32_bf16 v[16:19], v[172:175], v[202:205], v[16:19]
	v_mfma_f32_16x16x32_bf16 v[4:7], v[164:167], v[210:213], v[4:7]
	v_mfma_f32_16x16x32_bf16 v[0:3], v[172:175], v[210:213], v[0:3]
	s_setprio 0
	s_barrier
	s_add_i32 s62, s62, 2
	s_add_u32 s10, s10, 0x100
	s_addc_u32 s11, s11, 0
	s_add_u32 s54, s54, 0x100
	s_addc_u32 s59, s59, 0
	s_cmp_gt_u32 s62, 61
	s_cbranch_scc0 .LBB0_832
	s_and_b64 vcc, exec, s[20:21]
	s_cbranch_vccz .LBB0_835
	s_barrier
